# re-test of v36 after its launch-to-launch divergence
# speedup vs baseline: 1.0131x; 1.0131x over previous
; __global__ void __launch_bounds__(NWAVES * 64, 2) hymba_fwd(Args args) {
;     ...
;     XcdBarrier xbar = xcd_barrier_post((unsigned*)(ws + WS_CTL), MISC + 8);
;     ...
;     if (lo > hi) grid.sync();
.LBB0_5:
	s_or_b64 exec, exec, s[6:7]
	s_cmp_le_i32 s44, s45
	s_cbranch_scc1 .LBB0_17
	v_lshrrev_b32_e32 v1, 20, v0
	v_lshrrev_b32_e32 v0, 10, v0
	v_or_b32_e32 v0, v0, v1
	s_movk_i32 s6, 0x3ff
	v_and_or_b32 v0, v0, s6, v170
	v_cmp_eq_u32_e32 vcc, 0, v0
	s_barrier
	s_and_saveexec_b64 s[6:7], vcc
	s_cbranch_execz .LBB0_16
	buffer_wbl2 sc1
	s_waitcnt vmcnt(0)
	s_load_dwordx2 s[8:9], s[8:9], 0x58
	v_mov_b32_e32 v2, 0
	s_mov_b64 s[10:11], exec
	v_mbcnt_lo_u32_b32 v1, s10, 0
	v_mbcnt_hi_u32_b32 v1, s11, v1
	s_waitcnt lgkmcnt(0)
	global_load_dword v0, v2, s[8:9] offset:40 nt
	v_cmp_eq_u32_e32 vcc, 0, v1
	s_and_saveexec_b64 s[12:13], vcc
	s_cbranch_execz .LBB0_9
	s_bcnt1_i32_b64 s10, s[10:11]
	v_mov_b32_e32 v3, s10
	global_atomic_add v3, v2, v3, s[8:9] offset:32 sc0

; #define LAS __attribute__((address_space(3)))
; __device__ __forceinline__ unsigned pk2(float lo, float hi) { return f2bf(lo) | (f2bf(hi) << 16); }
; __device__ __forceinline__ void tr_item(const float* W, int ldw, int k0, int n0, bf16* WT, size_t drow0, int ldk, float scale, LAS float* scr, int lane) {
;     float wv[32];
; #pragma unroll
;     for (int i = 0; i < 32; ++i) wv[i] = W[(size_t)(k0 + 2 * i + (lane >> 5)) * ldw + n0 + (lane & 31)];
; #pragma unroll
;     for (int i = 0; i < 32; ++i) scr[(2 * i + (lane >> 5)) * 33 + (lane & 31)] = wv[i];
;     asm volatile("s_waitcnt lgkmcnt(0)" ::: "memory");
;     const int c = lane & 7;
; #pragma unroll
;     for (int j = 0; j < 4; ++j) { const int n = (lane >> 3) + 8 * j; const LAS float* s = scr + (8 * c) * 33 + n;
;         u32x4 o; o.x = pk2(s[0 * 33] * scale, s[1 * 33] * scale); o.y = pk2(s[2 * 33] * scale, s[3 * 33] * scale); o.z = pk2(s[4 * 33] * scale, s[5 * 33] * scale); o.w = pk2(s[6 * 33] * scale, s[7 * 33] * scale);
;         *(u32x4*)(WT + (drow0 + n) * ldk + k0 + 8 * c) = o; }
; __device__ __forceinline__ void p0_prologue(const P0Args& A, LAS unsigned char* lds, int gw, int NGW, int wave, int lane) {
;     ...
;         { const int isx = r >= I_L; if (isx) r -= I_L; const int n = r >> 3, k0 = 64 * ((r >> 2) & 1), n0 = 32 * (r & 3);
;           tr_item((isx ? A.lru_wx : A.lru_wa) + (size_t)n * 128 * 128, 128, k0, n0, A.Wlru + (size_t)n * 256 * 128, n0 + (isx ? 128 : 0), 128, 1.f, scr, lane); }
.LBB0_23:
	s_cmpk_gt_u32 s57, 0x1bff
	s_cbranch_scc0 .LBB0_41
	s_cmpk_gt_u32 s57, 0x47ff
	s_cbranch_scc0 .LBB0_38
	s_cmpk_gt_u32 s57, 0x5dff
	s_cbranch_scc0 .LBB0_35
	s_cmpk_gt_u32 s57, 0x65ff
	s_cbranch_scc0 .LBB0_32
	s_cmpk_gt_u32 s57, 0x66ff
	s_cbranch_scc0 .LBB0_29
	s_cmpk_gt_u32 s57, 0x673f
	s_cselect_b64 s[26:27], -1, 0
	s_and_b64 s[28:29], s[26:27], exec
	s_cselect_b32 s24, s31, 0xffff9900
	s_add_i32 s28, s24, s57
	s_lshr_b32 s24, s28, 3
	s_lshl_b32 s29, s28, 4
	s_lshl_b32 s28, s28, 5
	s_and_b32 s29, s29, 64
	s_and_b32 s28, s28, 0x60
	s_and_b64 s[26:27], s[26:27], exec
	s_cselect_b32 s36, 0x80, 0
	s_cselect_b32 s37, s23, s7
	s_cselect_b32 s58, s22, s6
	s_lshl_b64 s[26:27], s[24:25], 16
	s_add_u32 s58, s58, s26
	s_addc_u32 s37, s37, s27
	s_add_u32 s59, s16, s26
	s_addc_u32 s62, s17, s27
	s_or_b32 s24, s28, s36
	s_lshl_b32 s26, s28, 2
	s_add_u32 s26, s58, s26
	v_or_b32_e32 v0, s29, v3
	s_addc_u32 s27, s37, 0
	v_mov_b32_e32 v35, v1
	v_lshl_add_u64 v[44:45], s[26:27], 0, v[34:35]
	v_lshlrev_b32_e32 v0, 9, v0
	v_lshl_add_u64 v[44:45], v[44:45], 0, v[0:1]
	v_add_co_u32_e32 v46, vcc, s34, v44
	s_lshl_b32 s26, s29, 1
	s_nop 0
	v_addc_co_u32_e32 v47, vcc, 0, v45, vcc
	flat_load_dword v0, v[44:45] nt
	flat_load_dword v33, v[44:45] offset:1024 nt
	flat_load_dword v35, v[44:45] offset:2048 nt
	flat_load_dword v43, v[44:45] offset:3072 nt
	flat_load_dword v50, v[46:47] nt
	flat_load_dword v51, v[46:47] offset:1024 nt
	flat_load_dword v52, v[46:47] offset:2048 nt
	flat_load_dword v53, v[46:47] offset:3072 nt
	v_add_co_u32_e32 v46, vcc, s35, v44
	s_add_u32 s26, s59, s26
	s_nop 0
	v_addc_co_u32_e32 v47, vcc, 0, v45, vcc
	v_add_co_u32_e32 v48, vcc, s39, v44
	s_addc_u32 s27, s62, 0
	s_nop 0
	v_addc_co_u32_e32 v49, vcc, 0, v45, vcc
	flat_load_dword v54, v[46:47] nt
	flat_load_dword v55, v[46:47] offset:1024 nt
	flat_load_dword v56, v[46:47] offset:2048 nt
	flat_load_dword v57, v[46:47] offset:3072 nt
	flat_load_dword v58, v[48:49] nt
	flat_load_dword v59, v[48:49] offset:1024 nt
	flat_load_dword v60, v[48:49] offset:2048 nt
	flat_load_dword v61, v[48:49] offset:3072 nt
	v_add_co_u32_e32 v46, vcc, s48, v44
	s_nop 1
	v_addc_co_u32_e32 v47, vcc, 0, v45, vcc
	v_add_co_u32_e32 v48, vcc, s49, v44
	s_nop 1
	v_addc_co_u32_e32 v49, vcc, 0, v45, vcc
	flat_load_dword v62, v[46:47] nt
	flat_load_dword v63, v[46:47] offset:1024 nt
	flat_load_dword v64, v[46:47] offset:2048 nt
	flat_load_dword v65, v[46:47] offset:3072 nt
	flat_load_dword v66, v[48:49] nt
	flat_load_dword v67, v[48:49] offset:1024 nt
	flat_load_dword v68, v[48:49] offset:2048 nt
	s_nop 0
	flat_load_dword v48, v[48:49] offset:3072 nt
	v_add_co_u32_e32 v46, vcc, s50, v44
	s_nop 1
	v_addc_co_u32_e32 v47, vcc, 0, v45, vcc
	v_add_co_u32_e32 v44, vcc, s51, v44
	s_nop 1
	v_addc_co_u32_e32 v45, vcc, 0, v45, vcc
	flat_load_dword v49, v[46:47] nt
	flat_load_dword v69, v[46:47] offset:1024 nt
	flat_load_dword v70, v[46:47] offset:2048 nt
	s_nop 0
	flat_load_dword v46, v[46:47] offset:3072 nt
	s_nop 0
	flat_load_dword v47, v[44:45] nt
	flat_load_dword v71, v[44:45] offset:1024 nt
	flat_load_dword v72, v[44:45] offset:2048 nt
	s_nop 0
	flat_load_dword v44, v[44:45] offset:3072 nt
	s_waitcnt vmcnt(0) lgkmcnt(0)
	ds_write2_b32 v5, v0, v33 offset1:66
	ds_write2_b32 v5, v35, v43 offset0:132 offset1:198
	ds_write2_b32 v9, v50, v51 offset0:8 offset1:74
	ds_write2_b32 v9, v52, v53 offset0:140 offset1:206
	ds_write2_b32 v36, v54, v55 offset0:16 offset1:82
	ds_write2_b32 v36, v56, v57 offset0:148 offset1:214
	ds_write2_b32 v37, v58, v59 offset0:24 offset1:90
	ds_write2_b32 v37, v60, v61 offset0:156 offset1:222
	ds_write2_b32 v38, v62, v63 offset0:32 offset1:98
	ds_write2_b32 v38, v64, v65 offset0:164 offset1:230
	ds_write2_b32 v39, v66, v67 offset0:40 offset1:106
	ds_write2_b32 v39, v68, v48 offset0:172 offset1:238
	ds_write2_b32 v40, v49, v69 offset0:48 offset1:114
	ds_write2_b32 v40, v70, v46 offset0:180 offset1:246
	ds_write2_b32 v41, v47, v71 offset0:56 offset1:122
	ds_write2_b32 v41, v72, v44 offset0:188 offset1:254
	s_waitcnt lgkmcnt(0)
	ds_read2_b32 v[48:49], v7 offset1:8
	ds_read2_b32 v[52:53], v7 offset0:33 offset1:41
	ds_read2_b32 v[54:55], v7 offset0:66 offset1:74
	ds_read2_b32 v[56:57], v7 offset0:99 offset1:107
	v_mov_b32_e32 v33, v1
	s_waitcnt lgkmcnt(3)
	v_bfe_u32 v0, v48, 16, 1
	v_lshl_add_u64 v[50:51], s[26:27], 0, v[32:33]
	v_add3_u32 v0, v48, v0, s52
	s_waitcnt lgkmcnt(2)
	v_bfe_u32 v33, v52, 16, 1
	ds_read2_b32 v[58:59], v7 offset0:132 offset1:140
	v_lshrrev_b32_e32 v0, 16, v0
	v_add3_u32 v33, v52, v33, s52
	ds_read2_b32 v[60:61], v7 offset0:165 offset1:173
	v_and_or_b32 v44, v33, s53, v0
	s_waitcnt lgkmcnt(3)
	v_bfe_u32 v0, v54, 16, 1
	v_add3_u32 v0, v54, v0, s52
	s_waitcnt lgkmcnt(2)
	v_bfe_u32 v33, v56, 16, 1
	ds_read2_b32 v[62:63], v7 offset0:198 offset1:206
	v_lshrrev_b32_e32 v0, 16, v0
	v_add3_u32 v33, v56, v33, s52
	ds_read2_b32 v[64:65], v7 offset0:231 offset1:239
	v_and_or_b32 v45, v33, s53, v0
	s_waitcnt lgkmcnt(3)
	v_bfe_u32 v0, v58, 16, 1
	v_add3_u32 v0, v58, v0, s52
	s_waitcnt lgkmcnt(2)
	v_bfe_u32 v33, v60, 16, 1
	v_lshrrev_b32_e32 v0, 16, v0
	v_add3_u32 v33, v60, v33, s52
	v_and_or_b32 v46, v33, s53, v0
	s_waitcnt lgkmcnt(1)
	v_bfe_u32 v0, v62, 16, 1
	v_add3_u32 v0, v62, v0, s52
	s_waitcnt lgkmcnt(0)
; #define LAS __attribute__((address_space(3)))
; __device__ __forceinline__ unsigned pk2(float lo, float hi) { return f2bf(lo) | (f2bf(hi) << 16); }
; __device__ __forceinline__ void tr_item(const float* W, int ldw, int k0, int n0, bf16* WT, size_t drow0, int ldk, float scale, LAS float* scr, int lane) {
;     float wv[32];
; #pragma unroll
;     for (int i = 0; i < 32; ++i) wv[i] = W[(size_t)(k0 + 2 * i + (lane >> 5)) * ldw + n0 + (lane & 31)];
; #pragma unroll
;     for (int i = 0; i < 32; ++i) scr[(2 * i + (lane >> 5)) * 33 + (lane & 31)] = wv[i];
;     asm volatile("s_waitcnt lgkmcnt(0)" ::: "memory");
;     const int c = lane & 7;
; #pragma unroll
;     for (int j = 0; j < 4; ++j) { const int n = (lane >> 3) + 8 * j; const LAS float* s = scr + (8 * c) * 33 + n;
;         u32x4 o; o.x = pk2(s[0 * 33] * scale, s[1 * 33] * scale); o.y = pk2(s[2 * 33] * scale, s[3 * 33] * scale); o.z = pk2(s[4 * 33] * scale, s[5 * 33] * scale); o.w = pk2(s[6 * 33] * scale, s[7 * 33] * scale);
;         *(u32x4*)(WT + (drow0 + n) * ldk + k0 + 8 * c) = o; }
; __device__ __forceinline__ void p0_prologue(const P0Args& A, LAS unsigned char* lds, int gw, int NGW, int wave, int lane) {
;     ...
;         if (r < I_PP) { const int nb = D / 32, k0 = 64 * (r / nb), n0 = 32 * (r % nb); tr_item(A.w_pp, D, k0, n0, A.Wpp, n0, PLE, 1.f, scr, lane); continue; } r -= I_PP;
	v_bfe_u32 v33, v64, 16, 1
	v_lshrrev_b32_e32 v0, 16, v0
	v_add3_u32 v33, v64, v33, s52
	v_and_or_b32 v47, v33, s53, v0
	v_or_b32_e32 v0, s24, v2
	v_lshlrev_b32_e32 v0, 8, v0
	v_lshl_add_u64 v[66:67], v[50:51], 0, v[0:1]
	v_bfe_u32 v0, v49, 16, 1
	v_add3_u32 v0, v49, v0, s52
	v_bfe_u32 v33, v53, 16, 1
	v_lshrrev_b32_e32 v0, 16, v0
	v_add3_u32 v33, v53, v33, s52
	global_store_dwordx4 v[66:67], v[44:47], off
	ds_read2_b32 v[48:49], v7 offset0:16 offset1:24
	s_mov_b64 s[26:27], 0
	v_and_or_b32 v44, v33, s53, v0
	v_bfe_u32 v0, v55, 16, 1
	v_add3_u32 v0, v55, v0, s52
	v_bfe_u32 v33, v57, 16, 1
	v_lshrrev_b32_e32 v0, 16, v0
	v_add3_u32 v33, v57, v33, s52
	v_and_or_b32 v45, v33, s53, v0
	v_bfe_u32 v0, v59, 16, 1
	v_add3_u32 v0, v59, v0, s52
	v_bfe_u32 v33, v61, 16, 1
	v_lshrrev_b32_e32 v0, 16, v0
	v_add3_u32 v33, v61, v33, s52
	v_and_or_b32 v46, v33, s53, v0
	v_bfe_u32 v0, v63, 16, 1
	v_add3_u32 v0, v63, v0, s52
	v_bfe_u32 v33, v65, 16, 1
	v_lshrrev_b32_e32 v0, 16, v0
	v_add3_u32 v33, v65, v33, s52
	v_and_or_b32 v47, v33, s53, v0
	v_or_b32_e32 v0, s24, v4
	v_lshlrev_b32_e32 v0, 8, v0
	v_lshl_add_u64 v[52:53], v[50:51], 0, v[0:1]
	global_store_dwordx4 v[52:53], v[44:47], off
	ds_read2_b32 v[52:53], v7 offset0:49 offset1:57
	ds_read2_b32 v[54:55], v7 offset0:82 offset1:90
	ds_read2_b32 v[56:57], v7 offset0:115 offset1:123
	s_waitcnt lgkmcnt(3)
	v_bfe_u32 v0, v48, 16, 1
	v_add3_u32 v0, v48, v0, s52
	s_waitcnt lgkmcnt(2)
	v_bfe_u32 v33, v52, 16, 1
	ds_read2_b32 v[58:59], v7 offset0:148 offset1:156
	v_lshrrev_b32_e32 v0, 16, v0
	v_add3_u32 v33, v52, v33, s52
	ds_read2_b32 v[60:61], v7 offset0:181 offset1:189
	v_and_or_b32 v44, v33, s53, v0
	s_waitcnt lgkmcnt(3)
	v_bfe_u32 v0, v54, 16, 1
	v_add3_u32 v0, v54, v0, s52
	s_waitcnt lgkmcnt(2)
	v_bfe_u32 v33, v56, 16, 1
	ds_read2_b32 v[62:63], v7 offset0:214 offset1:222
	v_lshrrev_b32_e32 v0, 16, v0
	v_add3_u32 v33, v56, v33, s52
	ds_read2_b32 v[64:65], v7 offset0:247 offset1:255
	v_and_or_b32 v45, v33, s53, v0
	s_waitcnt lgkmcnt(3)
	v_bfe_u32 v0, v58, 16, 1
	v_add3_u32 v0, v58, v0, s52
	s_waitcnt lgkmcnt(2)
	v_bfe_u32 v33, v60, 16, 1
	v_lshrrev_b32_e32 v0, 16, v0
	v_add3_u32 v33, v60, v33, s52
	v_and_or_b32 v46, v33, s53, v0
	s_waitcnt lgkmcnt(1)
	v_bfe_u32 v0, v62, 16, 1
	v_add3_u32 v0, v62, v0, s52
	s_waitcnt lgkmcnt(0)
	v_bfe_u32 v33, v64, 16, 1
	v_lshrrev_b32_e32 v0, 16, v0
	v_add3_u32 v33, v64, v33, s52
	v_and_or_b32 v47, v33, s53, v0
	v_or_b32_e32 v0, s24, v6
	v_lshlrev_b32_e32 v0, 8, v0
	v_lshl_add_u64 v[66:67], v[50:51], 0, v[0:1]
	v_bfe_u32 v0, v49, 16, 1
	v_add3_u32 v0, v49, v0, s52
	v_bfe_u32 v33, v53, 16, 1
	v_lshrrev_b32_e32 v0, 16, v0
	v_add3_u32 v33, v53, v33, s52
	global_store_dwordx4 v[66:67], v[44:47], off
	s_nop 1
	v_and_or_b32 v44, v33, s53, v0
	v_bfe_u32 v0, v55, 16, 1
	v_add3_u32 v0, v55, v0, s52
	v_bfe_u32 v33, v57, 16, 1
	v_lshrrev_b32_e32 v0, 16, v0
	v_add3_u32 v33, v57, v33, s52
	v_and_or_b32 v45, v33, s53, v0
	v_bfe_u32 v0, v59, 16, 1
	v_add3_u32 v0, v59, v0, s52
	v_bfe_u32 v33, v61, 16, 1
	v_lshrrev_b32_e32 v0, 16, v0
	v_add3_u32 v33, v61, v33, s52
	v_and_or_b32 v46, v33, s53, v0
	v_bfe_u32 v0, v63, 16, 1
	v_add3_u32 v0, v63, v0, s52
	v_bfe_u32 v33, v65, 16, 1
	v_lshrrev_b32_e32 v0, 16, v0
	v_add3_u32 v33, v65, v33, s52
	v_and_or_b32 v47, v33, s53, v0
	v_or_b32_e32 v0, s24, v8
	v_lshlrev_b32_e32 v0, 8, v0
	v_lshl_add_u64 v[48:49], v[50:51], 0, v[0:1]
	global_store_dwordx4 v[48:49], v[44:47], off
	s_waitcnt lgkmcnt(0)
.LBB0_29:
	s_andn2_b64 vcc, exec, s[26:27]
	s_cbranch_vccnz .LBB0_31
	s_and_b32 s24, s57, 0x7fc0
	s_add_i32 s26, s24, 0xffff9a00
	s_and_b32 s28, s3, 0x7e0
	v_or_b32_e32 v0, s26, v3
	s_lshl_b32 s24, s28, 2
	v_or_b32_e32 v48, 2, v0
	v_mov_b32_e32 v49, v1
	v_or_b32_e32 v50, 4, v0
	v_mov_b32_e32 v51, v1
	v_or_b32_e32 v52, 6, v0
	v_mov_b32_e32 v53, v1
	v_or_b32_e32 v54, 8, v0
	v_mov_b32_e32 v55, v1
	v_or_b32_e32 v56, 10, v0
	v_mov_b32_e32 v57, v1
	v_or_b32_e32 v58, 12, v0
	v_mov_b32_e32 v59, v1
	v_lshl_add_u64 v[44:45], v[10:11], 0, s[24:25]
	v_lshlrev_b64 v[46:47], 13, v[0:1]
	v_lshlrev_b64 v[48:49], 13, v[48:49]
	v_lshlrev_b64 v[50:51], 13, v[50:51]
	v_lshlrev_b64 v[52:53], 13, v[52:53]
	v_lshlrev_b64 v[54:55], 13, v[54:55]
	v_lshlrev_b64 v[56:57], 13, v[56:57]
	v_lshlrev_b64 v[58:59], 13, v[58:59]
	v_or_b32_e32 v60, 14, v0
	v_mov_b32_e32 v61, v1
	v_lshl_add_u64 v[46:47], v[44:45], 0, v[46:47]
	v_lshl_add_u64 v[48:49], v[44:45], 0, v[48:49]
	v_lshl_add_u64 v[50:51], v[44:45], 0, v[50:51]
	v_lshl_add_u64 v[52:53], v[44:45], 0, v[52:53]
	v_lshl_add_u64 v[54:55], v[44:45], 0, v[54:55]
	v_lshl_add_u64 v[56:57], v[44:45], 0, v[56:57]
	v_lshl_add_u64 v[58:59], v[44:45], 0, v[58:59]
	v_lshlrev_b64 v[60:61], 13, v[60:61]
	v_lshl_add_u64 v[60:61], v[44:45], 0, v[60:61]
	flat_load_dword v33, v[46:47] nt
	flat_load_dword v35, v[48:49] nt
	flat_load_dword v43, v[50:51] nt
	flat_load_dword v62, v[52:53] nt
	flat_load_dword v63, v[54:55] nt
	flat_load_dword v64, v[56:57] nt
	flat_load_dword v65, v[58:59] nt
	flat_load_dword v66, v[60:61] nt
	v_or_b32_e32 v46, 16, v0
	v_mov_b32_e32 v47, v1
	v_or_b32_e32 v48, 18, v0
	v_mov_b32_e32 v49, v1
	v_or_b32_e32 v50, 20, v0
	v_mov_b32_e32 v51, v1
	v_or_b32_e32 v52, 22, v0
	v_mov_b32_e32 v53, v1
	v_or_b32_e32 v54, 24, v0
	v_mov_b32_e32 v55, v1
	v_or_b32_e32 v56, 26, v0
	v_mov_b32_e32 v57, v1
	v_or_b32_e32 v58, 28, v0
	v_mov_b32_e32 v59, v1
	v_lshlrev_b64 v[46:47], 13, v[46:47]
	v_lshlrev_b64 v[48:49], 13, v[48:49]
	v_lshlrev_b64 v[50:51], 13, v[50:51]
	v_lshlrev_b64 v[52:53], 13, v[52:53]
	v_lshlrev_b64 v[54:55], 13, v[54:55]
	v_lshlrev_b64 v[56:57], 13, v[56:57]
	v_lshlrev_b64 v[58:59], 13, v[58:59]
	v_or_b32_e32 v60, 30, v0
	v_mov_b32_e32 v61, v1
; __device__ __forceinline__ void tr_item(const float* W, int ldw, int k0, int n0, bf16* WT, size_t drow0, int ldk, float scale, LAS float* scr, int lane) {
;     ...
;     for (int i = 0; i < 32; ++i) wv[i] = W[(size_t)(k0 + 2 * i + (lane >> 5)) * ldw + n0 + (lane & 31)];
; #pragma unroll
;     for (int i = 0; i < 32; ++i) scr[(2 * i + (lane >> 5)) * 33 + (lane & 31)] = wv[i];
;     asm volatile("s_waitcnt lgkmcnt(0)" ::: "memory");
	v_lshl_add_u64 v[46:47], v[44:45], 0, v[46:47]
	v_lshl_add_u64 v[48:49], v[44:45], 0, v[48:49]
	v_lshl_add_u64 v[50:51], v[44:45], 0, v[50:51]
	v_lshl_add_u64 v[52:53], v[44:45], 0, v[52:53]
	v_lshl_add_u64 v[54:55], v[44:45], 0, v[54:55]
	v_lshl_add_u64 v[56:57], v[44:45], 0, v[56:57]
	v_lshl_add_u64 v[58:59], v[44:45], 0, v[58:59]
	v_lshlrev_b64 v[60:61], 13, v[60:61]
	v_lshl_add_u64 v[60:61], v[44:45], 0, v[60:61]
	flat_load_dword v67, v[46:47] nt
	flat_load_dword v68, v[48:49] nt
	flat_load_dword v69, v[50:51] nt
	flat_load_dword v70, v[52:53] nt
	flat_load_dword v71, v[54:55] nt
	flat_load_dword v72, v[56:57] nt
	flat_load_dword v73, v[58:59] nt
	flat_load_dword v74, v[60:61] nt
	v_or_b32_e32 v46, 32, v0
	v_mov_b32_e32 v47, v1
	v_or_b32_e32 v48, 34, v0
	v_mov_b32_e32 v49, v1
	v_or_b32_e32 v50, 36, v0
	v_mov_b32_e32 v51, v1
	v_or_b32_e32 v52, 38, v0
	v_mov_b32_e32 v53, v1
	v_or_b32_e32 v54, 40, v0
	v_mov_b32_e32 v55, v1
	v_or_b32_e32 v56, 42, v0
	v_mov_b32_e32 v57, v1
	v_or_b32_e32 v58, 44, v0
	v_mov_b32_e32 v59, v1
	v_lshlrev_b64 v[46:47], 13, v[46:47]
	v_lshlrev_b64 v[48:49], 13, v[48:49]
	v_lshlrev_b64 v[50:51], 13, v[50:51]
	v_lshlrev_b64 v[52:53], 13, v[52:53]
	v_lshlrev_b64 v[54:55], 13, v[54:55]
	v_lshlrev_b64 v[56:57], 13, v[56:57]
	v_lshlrev_b64 v[58:59], 13, v[58:59]
	v_or_b32_e32 v60, 46, v0
	v_mov_b32_e32 v61, v1
	v_lshl_add_u64 v[46:47], v[44:45], 0, v[46:47]
	v_lshl_add_u64 v[48:49], v[44:45], 0, v[48:49]
	v_lshl_add_u64 v[50:51], v[44:45], 0, v[50:51]
	v_lshl_add_u64 v[52:53], v[44:45], 0, v[52:53]
	v_lshl_add_u64 v[54:55], v[44:45], 0, v[54:55]
	v_lshl_add_u64 v[56:57], v[44:45], 0, v[56:57]
	v_lshl_add_u64 v[58:59], v[44:45], 0, v[58:59]
	v_lshlrev_b64 v[60:61], 13, v[60:61]
	v_lshl_add_u64 v[60:61], v[44:45], 0, v[60:61]
	flat_load_dword v75, v[46:47] nt
	flat_load_dword v76, v[48:49] nt
	flat_load_dword v77, v[50:51] nt
	flat_load_dword v78, v[52:53] nt
	flat_load_dword v79, v[54:55] nt
	flat_load_dword v80, v[56:57] nt
	flat_load_dword v81, v[58:59] nt
	flat_load_dword v82, v[60:61] nt
	v_or_b32_e32 v46, 48, v0
	v_mov_b32_e32 v47, v1
	v_or_b32_e32 v48, 50, v0
	v_mov_b32_e32 v49, v1
	v_or_b32_e32 v50, 52, v0
	v_mov_b32_e32 v51, v1
	v_or_b32_e32 v52, 54, v0
	v_mov_b32_e32 v53, v1
	v_or_b32_e32 v54, 56, v0
	v_mov_b32_e32 v55, v1
	v_or_b32_e32 v56, 58, v0
	v_mov_b32_e32 v57, v1
	v_or_b32_e32 v58, 60, v0
	v_mov_b32_e32 v59, v1
	v_or_b32_e32 v0, 62, v0
	v_lshlrev_b64 v[46:47], 13, v[46:47]
	v_lshlrev_b64 v[48:49], 13, v[48:49]
	v_lshlrev_b64 v[50:51], 13, v[50:51]
	v_lshlrev_b64 v[52:53], 13, v[52:53]
	v_lshlrev_b64 v[54:55], 13, v[54:55]
	v_lshlrev_b64 v[56:57], 13, v[56:57]
	v_lshlrev_b64 v[58:59], 13, v[58:59]
	v_lshlrev_b64 v[60:61], 13, v[0:1]
	v_lshl_add_u64 v[46:47], v[44:45], 0, v[46:47]
	v_lshl_add_u64 v[48:49], v[44:45], 0, v[48:49]
	v_lshl_add_u64 v[50:51], v[44:45], 0, v[50:51]
	v_lshl_add_u64 v[52:53], v[44:45], 0, v[52:53]
	v_lshl_add_u64 v[54:55], v[44:45], 0, v[54:55]
	v_lshl_add_u64 v[56:57], v[44:45], 0, v[56:57]
	v_lshl_add_u64 v[58:59], v[44:45], 0, v[58:59]
	v_lshl_add_u64 v[44:45], v[44:45], 0, v[60:61]
	flat_load_dword v0, v[46:47] nt
	s_nop 0
	flat_load_dword v46, v[48:49] nt
	flat_load_dword v47, v[50:51] nt
	s_nop 0
	flat_load_dword v48, v[52:53] nt
	flat_load_dword v49, v[54:55] nt
	flat_load_dword v50, v[56:57] nt
	flat_load_dword v51, v[58:59] nt
	s_nop 0
	flat_load_dword v44, v[44:45] nt
	s_waitcnt vmcnt(0) lgkmcnt(0)
	ds_write2_b32 v5, v33, v35 offset1:66
	ds_write2_b32 v5, v43, v62 offset0:132 offset1:198
	ds_write2_b32 v9, v63, v64 offset0:8 offset1:74
	ds_write2_b32 v9, v65, v66 offset0:140 offset1:206
	ds_write2_b32 v36, v67, v68 offset0:16 offset1:82
	ds_write2_b32 v36, v69, v70 offset0:148 offset1:214
	ds_write2_b32 v37, v71, v72 offset0:24 offset1:90
	ds_write2_b32 v37, v73, v74 offset0:156 offset1:222
	ds_write2_b32 v38, v75, v76 offset0:32 offset1:98
	ds_write2_b32 v38, v77, v78 offset0:164 offset1:230
	ds_write2_b32 v39, v79, v80 offset0:40 offset1:106
	ds_write2_b32 v39, v81, v82 offset0:172 offset1:238
	ds_write2_b32 v40, v0, v46 offset0:48 offset1:114
	ds_write2_b32 v40, v47, v48 offset0:180 offset1:246
	ds_write2_b32 v41, v49, v50 offset0:56 offset1:122
	ds_write2_b32 v41, v51, v44 offset0:188 offset1:254
	s_waitcnt lgkmcnt(0)
	ds_read2_b32 v[48:49], v7 offset1:8
	ds_read2_b32 v[52:53], v7 offset0:33 offset1:41
	ds_read2_b32 v[54:55], v7 offset0:66 offset1:74
	ds_read2_b32 v[56:57], v7 offset0:99 offset1:107
	ds_read2_b32 v[58:59], v7 offset0:132 offset1:140
	s_waitcnt lgkmcnt(4)
; #define LAS __attribute__((address_space(3)))
; __device__ __forceinline__ unsigned pk2(float lo, float hi) { return f2bf(lo) | (f2bf(hi) << 16); }
; __device__ __forceinline__ void tr_item(const float* W, int ldw, int k0, int n0, bf16* WT, size_t drow0, int ldk, float scale, LAS float* scr, int lane) {
;     ...
;     asm volatile("s_waitcnt lgkmcnt(0)" ::: "memory");
;     const int c = lane & 7;
; #pragma unroll
;     for (int j = 0; j < 4; ++j) { const int n = (lane >> 3) + 8 * j; const LAS float* s = scr + (8 * c) * 33 + n;
;         u32x4 o; o.x = pk2(s[0 * 33] * scale, s[1 * 33] * scale); o.y = pk2(s[2 * 33] * scale, s[3 * 33] * scale); o.z = pk2(s[4 * 33] * scale, s[5 * 33] * scale); o.w = pk2(s[6 * 33] * scale, s[7 * 33] * scale);
;         *(u32x4*)(WT + (drow0 + n) * ldk + k0 + 8 * c) = o; }
	v_bfe_u32 v0, v48, 16, 1
	v_add3_u32 v0, v48, v0, s52
	s_waitcnt lgkmcnt(3)
	v_bfe_u32 v33, v52, 16, 1
	v_lshrrev_b32_e32 v0, 16, v0
	v_add3_u32 v33, v52, v33, s52
	ds_read2_b32 v[60:61], v7 offset0:165 offset1:173
	v_and_or_b32 v44, v33, s53, v0
	s_waitcnt lgkmcnt(3)
	v_bfe_u32 v0, v54, 16, 1
	v_add3_u32 v0, v54, v0, s52
	s_waitcnt lgkmcnt(2)
	v_bfe_u32 v33, v56, 16, 1
	ds_read2_b32 v[62:63], v7 offset0:198 offset1:206
	v_lshrrev_b32_e32 v0, 16, v0
	v_add3_u32 v33, v56, v33, s52
	ds_read2_b32 v[64:65], v7 offset0:231 offset1:239
	v_and_or_b32 v45, v33, s53, v0
	s_waitcnt lgkmcnt(3)
	v_bfe_u32 v0, v58, 16, 1
	v_add3_u32 v0, v58, v0, s52
	s_waitcnt lgkmcnt(2)
	v_bfe_u32 v33, v60, 16, 1
	v_lshrrev_b32_e32 v0, 16, v0
	v_add3_u32 v33, v60, v33, s52
	v_and_or_b32 v46, v33, s53, v0
	s_waitcnt lgkmcnt(1)
	v_bfe_u32 v0, v62, 16, 1
	v_add3_u32 v0, v62, v0, s52
	s_waitcnt lgkmcnt(0)
	v_bfe_u32 v33, v64, 16, 1
	v_lshrrev_b32_e32 v0, 16, v0
	v_add3_u32 v33, v64, v33, s52
	s_mov_b32 s27, s25
	v_and_or_b32 v47, v33, s53, v0
	v_or_b32_e32 v0, s28, v2
	v_lshl_add_u64 v[50:51], s[26:27], 1, v[12:13]
	v_lshlrev_b32_e32 v0, 9, v0
	v_lshl_add_u64 v[66:67], v[50:51], 0, v[0:1]
	v_bfe_u32 v0, v49, 16, 1
	v_add3_u32 v0, v49, v0, s52
	v_bfe_u32 v33, v53, 16, 1
	v_lshrrev_b32_e32 v0, 16, v0
	v_add3_u32 v33, v53, v33, s52
	global_store_dwordx4 v[66:67], v[44:47], off
	ds_read2_b32 v[48:49], v7 offset0:16 offset1:24
	s_nop 0
	v_and_or_b32 v44, v33, s53, v0
	v_bfe_u32 v0, v55, 16, 1
	v_add3_u32 v0, v55, v0, s52
	v_bfe_u32 v33, v57, 16, 1
	v_lshrrev_b32_e32 v0, 16, v0
	v_add3_u32 v33, v57, v33, s52
	v_and_or_b32 v45, v33, s53, v0
	v_bfe_u32 v0, v59, 16, 1
	v_add3_u32 v0, v59, v0, s52
	v_bfe_u32 v33, v61, 16, 1
	v_lshrrev_b32_e32 v0, 16, v0
	v_add3_u32 v33, v61, v33, s52
	v_and_or_b32 v46, v33, s53, v0
	v_bfe_u32 v0, v63, 16, 1
	v_add3_u32 v0, v63, v0, s52
	v_bfe_u32 v33, v65, 16, 1
	v_lshrrev_b32_e32 v0, 16, v0
	v_add3_u32 v33, v65, v33, s52
	v_and_or_b32 v47, v33, s53, v0
	v_or_b32_e32 v0, s28, v4
	v_lshlrev_b32_e32 v0, 9, v0
	v_lshl_add_u64 v[52:53], v[50:51], 0, v[0:1]
	global_store_dwordx4 v[52:53], v[44:47], off
	ds_read2_b32 v[52:53], v7 offset0:49 offset1:57
	ds_read2_b32 v[54:55], v7 offset0:82 offset1:90
	ds_read2_b32 v[56:57], v7 offset0:115 offset1:123
	s_waitcnt lgkmcnt(3)
	v_bfe_u32 v0, v48, 16, 1
	v_add3_u32 v0, v48, v0, s52
	s_waitcnt lgkmcnt(2)
	v_bfe_u32 v33, v52, 16, 1
	ds_read2_b32 v[58:59], v7 offset0:148 offset1:156
	v_lshrrev_b32_e32 v0, 16, v0
	v_add3_u32 v33, v52, v33, s52
	ds_read2_b32 v[60:61], v7 offset0:181 offset1:189
	v_and_or_b32 v44, v33, s53, v0
	s_waitcnt lgkmcnt(3)
	v_bfe_u32 v0, v54, 16, 1
	v_add3_u32 v0, v54, v0, s52
	s_waitcnt lgkmcnt(2)
	v_bfe_u32 v33, v56, 16, 1
	ds_read2_b32 v[62:63], v7 offset0:214 offset1:222
	v_lshrrev_b32_e32 v0, 16, v0
	v_add3_u32 v33, v56, v33, s52
	ds_read2_b32 v[64:65], v7 offset0:247 offset1:255
	v_and_or_b32 v45, v33, s53, v0
	s_waitcnt lgkmcnt(3)
	v_bfe_u32 v0, v58, 16, 1
	v_add3_u32 v0, v58, v0, s52
	s_waitcnt lgkmcnt(2)
	v_bfe_u32 v33, v60, 16, 1
	v_lshrrev_b32_e32 v0, 16, v0
	v_add3_u32 v33, v60, v33, s52
	v_and_or_b32 v46, v33, s53, v0
	s_waitcnt lgkmcnt(1)
	v_bfe_u32 v0, v62, 16, 1
	v_add3_u32 v0, v62, v0, s52
	s_waitcnt lgkmcnt(0)
	v_bfe_u32 v33, v64, 16, 1
	v_lshrrev_b32_e32 v0, 16, v0
	v_add3_u32 v33, v64, v33, s52
	v_and_or_b32 v47, v33, s53, v0
	v_or_b32_e32 v0, s28, v6
	v_lshlrev_b32_e32 v0, 9, v0
	v_lshl_add_u64 v[66:67], v[50:51], 0, v[0:1]
	v_bfe_u32 v0, v49, 16, 1
	v_add3_u32 v0, v49, v0, s52
	v_bfe_u32 v33, v53, 16, 1
	v_lshrrev_b32_e32 v0, 16, v0
	v_add3_u32 v33, v53, v33, s52
	global_store_dwordx4 v[66:67], v[44:47], off
	s_nop 1
	v_and_or_b32 v44, v33, s53, v0
	v_bfe_u32 v0, v55, 16, 1
	v_add3_u32 v0, v55, v0, s52
	v_bfe_u32 v33, v57, 16, 1
	v_lshrrev_b32_e32 v0, 16, v0
	v_add3_u32 v33, v57, v33, s52
	v_and_or_b32 v45, v33, s53, v0
	v_bfe_u32 v0, v59, 16, 1
	v_add3_u32 v0, v59, v0, s52
	v_bfe_u32 v33, v61, 16, 1
	v_lshrrev_b32_e32 v0, 16, v0
	v_add3_u32 v33, v61, v33, s52
	v_and_or_b32 v46, v33, s53, v0
	v_bfe_u32 v0, v63, 16, 1
	v_add3_u32 v0, v63, v0, s52
	v_bfe_u32 v33, v65, 16, 1
	v_lshrrev_b32_e32 v0, 16, v0
	v_add3_u32 v33, v65, v33, s52
	v_and_or_b32 v47, v33, s53, v0
	v_or_b32_e32 v0, s28, v8
	v_lshlrev_b32_e32 v0, 9, v0
	v_lshl_add_u64 v[48:49], v[50:51], 0, v[0:1]
	global_store_dwordx4 v[48:49], v[44:47], off
	s_waitcnt lgkmcnt(0)

; #define LAS __attribute__((address_space(3)))
; __device__ __forceinline__ void tr_item(const float* W, int ldw, int k0, int n0, bf16* WT, size_t drow0, int ldk, float scale, LAS float* scr, int lane) {
;     float wv[32];
; #pragma unroll
;     for (int i = 0; i < 32; ++i) wv[i] = W[(size_t)(k0 + 2 * i + (lane >> 5)) * ldw + n0 + (lane & 31)];
; #pragma unroll
;     for (int i = 0; i < 32; ++i) scr[(2 * i + (lane >> 5)) * 33 + (lane & 31)] = wv[i];
; __device__ __forceinline__ void p0_prologue(const P0Args& A, LAS unsigned char* lds, int gw, int NGW, int wave, int lane) {
;     ...
;         if (r < I_PG) { const int nb = D / 32, k0 = 64 * (r / nb), n0 = 32 * (r % nb); tr_item(A.w_pg, D, k0, n0, A.Wpg, n0, D, 1.f, scr, lane); continue; } r -= I_PG;
.LBB0_32:
	s_andn2_b64 vcc, exec, s[26:27]
	s_cbranch_vccnz .LBB0_34
	s_and_b32 s24, s57, 0x7fc0
	s_add_i32 s26, s24, 0xffffa200
	s_and_b32 s28, s3, 0x7e0
	v_or_b32_e32 v0, s26, v3
	s_lshl_b32 s24, s28, 2
	v_or_b32_e32 v48, 2, v0
	v_mov_b32_e32 v49, v1
	v_or_b32_e32 v50, 4, v0
	v_mov_b32_e32 v51, v1
	v_or_b32_e32 v52, 6, v0
	v_mov_b32_e32 v53, v1
	v_or_b32_e32 v54, 8, v0
	v_mov_b32_e32 v55, v1
	v_or_b32_e32 v56, 10, v0
	v_mov_b32_e32 v57, v1
	v_or_b32_e32 v58, 12, v0
	v_mov_b32_e32 v59, v1
	v_lshl_add_u64 v[44:45], v[14:15], 0, s[24:25]
	v_lshlrev_b64 v[46:47], 13, v[0:1]
	v_lshlrev_b64 v[48:49], 13, v[48:49]
	v_lshlrev_b64 v[50:51], 13, v[50:51]
	v_lshlrev_b64 v[52:53], 13, v[52:53]
	v_lshlrev_b64 v[54:55], 13, v[54:55]
	v_lshlrev_b64 v[56:57], 13, v[56:57]
	v_lshlrev_b64 v[58:59], 13, v[58:59]
	v_or_b32_e32 v60, 14, v0
	v_mov_b32_e32 v61, v1
	v_lshl_add_u64 v[46:47], v[44:45], 0, v[46:47]
	v_lshl_add_u64 v[48:49], v[44:45], 0, v[48:49]
	v_lshl_add_u64 v[50:51], v[44:45], 0, v[50:51]
	v_lshl_add_u64 v[52:53], v[44:45], 0, v[52:53]
	v_lshl_add_u64 v[54:55], v[44:45], 0, v[54:55]
	v_lshl_add_u64 v[56:57], v[44:45], 0, v[56:57]
	v_lshl_add_u64 v[58:59], v[44:45], 0, v[58:59]
	v_lshlrev_b64 v[60:61], 13, v[60:61]
	v_lshl_add_u64 v[60:61], v[44:45], 0, v[60:61]
	flat_load_dword v33, v[46:47] nt
	flat_load_dword v35, v[48:49] nt
	flat_load_dword v43, v[50:51] nt
	flat_load_dword v62, v[52:53] nt
	flat_load_dword v63, v[54:55] nt
	flat_load_dword v64, v[56:57] nt
	flat_load_dword v65, v[58:59] nt
	flat_load_dword v66, v[60:61] nt
	v_or_b32_e32 v46, 16, v0
	v_mov_b32_e32 v47, v1
	v_or_b32_e32 v48, 18, v0
	v_mov_b32_e32 v49, v1
	v_or_b32_e32 v50, 20, v0
	v_mov_b32_e32 v51, v1
	v_or_b32_e32 v52, 22, v0
	v_mov_b32_e32 v53, v1
	v_or_b32_e32 v54, 24, v0
	v_mov_b32_e32 v55, v1
	v_or_b32_e32 v56, 26, v0
	v_mov_b32_e32 v57, v1
	v_or_b32_e32 v58, 28, v0
	v_mov_b32_e32 v59, v1
	v_lshlrev_b64 v[46:47], 13, v[46:47]
	v_lshlrev_b64 v[48:49], 13, v[48:49]
	v_lshlrev_b64 v[50:51], 13, v[50:51]
	v_lshlrev_b64 v[52:53], 13, v[52:53]
	v_lshlrev_b64 v[54:55], 13, v[54:55]
	v_lshlrev_b64 v[56:57], 13, v[56:57]
	v_lshlrev_b64 v[58:59], 13, v[58:59]
	v_or_b32_e32 v60, 30, v0
	v_mov_b32_e32 v61, v1
	v_lshl_add_u64 v[46:47], v[44:45], 0, v[46:47]
	v_lshl_add_u64 v[48:49], v[44:45], 0, v[48:49]
	v_lshl_add_u64 v[50:51], v[44:45], 0, v[50:51]
	v_lshl_add_u64 v[52:53], v[44:45], 0, v[52:53]
	v_lshl_add_u64 v[54:55], v[44:45], 0, v[54:55]
	v_lshl_add_u64 v[56:57], v[44:45], 0, v[56:57]
	v_lshl_add_u64 v[58:59], v[44:45], 0, v[58:59]
	v_lshlrev_b64 v[60:61], 13, v[60:61]
	v_lshl_add_u64 v[60:61], v[44:45], 0, v[60:61]
	flat_load_dword v67, v[46:47] nt
	flat_load_dword v68, v[48:49] nt
	flat_load_dword v69, v[50:51] nt
	flat_load_dword v70, v[52:53] nt
	flat_load_dword v71, v[54:55] nt
	flat_load_dword v72, v[56:57] nt
	flat_load_dword v73, v[58:59] nt
	flat_load_dword v74, v[60:61] nt
	v_or_b32_e32 v46, 32, v0
	v_mov_b32_e32 v47, v1
	v_or_b32_e32 v48, 34, v0
	v_mov_b32_e32 v49, v1
	v_or_b32_e32 v50, 36, v0
	v_mov_b32_e32 v51, v1
	v_or_b32_e32 v52, 38, v0
	v_mov_b32_e32 v53, v1
	v_or_b32_e32 v54, 40, v0
	v_mov_b32_e32 v55, v1
	v_or_b32_e32 v56, 42, v0
	v_mov_b32_e32 v57, v1
	v_or_b32_e32 v58, 44, v0
	v_mov_b32_e32 v59, v1
	v_lshlrev_b64 v[46:47], 13, v[46:47]
	v_lshlrev_b64 v[48:49], 13, v[48:49]
	v_lshlrev_b64 v[50:51], 13, v[50:51]
	v_lshlrev_b64 v[52:53], 13, v[52:53]
	v_lshlrev_b64 v[54:55], 13, v[54:55]
	v_lshlrev_b64 v[56:57], 13, v[56:57]
	v_lshlrev_b64 v[58:59], 13, v[58:59]
	v_or_b32_e32 v60, 46, v0
	v_mov_b32_e32 v61, v1
	v_lshl_add_u64 v[46:47], v[44:45], 0, v[46:47]
	v_lshl_add_u64 v[48:49], v[44:45], 0, v[48:49]
	v_lshl_add_u64 v[50:51], v[44:45], 0, v[50:51]
	v_lshl_add_u64 v[52:53], v[44:45], 0, v[52:53]
	v_lshl_add_u64 v[54:55], v[44:45], 0, v[54:55]
	v_lshl_add_u64 v[56:57], v[44:45], 0, v[56:57]
	v_lshl_add_u64 v[58:59], v[44:45], 0, v[58:59]
	v_lshlrev_b64 v[60:61], 13, v[60:61]
	v_lshl_add_u64 v[60:61], v[44:45], 0, v[60:61]
	flat_load_dword v75, v[46:47] nt
	flat_load_dword v76, v[48:49] nt
	flat_load_dword v77, v[50:51] nt
	flat_load_dword v78, v[52:53] nt
	flat_load_dword v79, v[54:55] nt
	flat_load_dword v80, v[56:57] nt
	flat_load_dword v81, v[58:59] nt
	flat_load_dword v82, v[60:61] nt
	v_or_b32_e32 v46, 48, v0
	v_mov_b32_e32 v47, v1
	v_or_b32_e32 v48, 50, v0
	v_mov_b32_e32 v49, v1
	v_or_b32_e32 v50, 52, v0
	v_mov_b32_e32 v51, v1
	v_or_b32_e32 v52, 54, v0
	v_mov_b32_e32 v53, v1
	v_or_b32_e32 v54, 56, v0
	v_mov_b32_e32 v55, v1
	v_or_b32_e32 v56, 58, v0
	v_mov_b32_e32 v57, v1
	v_or_b32_e32 v58, 60, v0
	v_mov_b32_e32 v59, v1
	v_or_b32_e32 v0, 62, v0
	v_lshlrev_b64 v[46:47], 13, v[46:47]
	v_lshlrev_b64 v[48:49], 13, v[48:49]
	v_lshlrev_b64 v[50:51], 13, v[50:51]
	v_lshlrev_b64 v[52:53], 13, v[52:53]
	v_lshlrev_b64 v[54:55], 13, v[54:55]
	v_lshlrev_b64 v[56:57], 13, v[56:57]
	v_lshlrev_b64 v[58:59], 13, v[58:59]
	v_lshlrev_b64 v[60:61], 13, v[0:1]
	v_lshl_add_u64 v[46:47], v[44:45], 0, v[46:47]
	v_lshl_add_u64 v[48:49], v[44:45], 0, v[48:49]
	v_lshl_add_u64 v[50:51], v[44:45], 0, v[50:51]
	v_lshl_add_u64 v[52:53], v[44:45], 0, v[52:53]
	v_lshl_add_u64 v[54:55], v[44:45], 0, v[54:55]
	v_lshl_add_u64 v[56:57], v[44:45], 0, v[56:57]
	v_lshl_add_u64 v[58:59], v[44:45], 0, v[58:59]
	v_lshl_add_u64 v[44:45], v[44:45], 0, v[60:61]
	flat_load_dword v0, v[46:47] nt
	s_nop 0
	flat_load_dword v46, v[48:49] nt
	flat_load_dword v47, v[50:51] nt
	s_nop 0
	flat_load_dword v48, v[52:53] nt
	flat_load_dword v49, v[54:55] nt
	flat_load_dword v50, v[56:57] nt
	flat_load_dword v51, v[58:59] nt
	s_nop 0
	flat_load_dword v44, v[44:45] nt
	s_waitcnt vmcnt(0) lgkmcnt(0)
; #define LAS __attribute__((address_space(3)))
; __device__ __forceinline__ unsigned pk2(float lo, float hi) { return f2bf(lo) | (f2bf(hi) << 16); }
; __device__ __forceinline__ void tr_item(const float* W, int ldw, int k0, int n0, bf16* WT, size_t drow0, int ldk, float scale, LAS float* scr, int lane) {
;     ...
;     for (int i = 0; i < 32; ++i) scr[(2 * i + (lane >> 5)) * 33 + (lane & 31)] = wv[i];
;     asm volatile("s_waitcnt lgkmcnt(0)" ::: "memory");
;     const int c = lane & 7;
; #pragma unroll
;     for (int j = 0; j < 4; ++j) { const int n = (lane >> 3) + 8 * j; const LAS float* s = scr + (8 * c) * 33 + n;
;         u32x4 o; o.x = pk2(s[0 * 33] * scale, s[1 * 33] * scale); o.y = pk2(s[2 * 33] * scale, s[3 * 33] * scale); o.z = pk2(s[4 * 33] * scale, s[5 * 33] * scale); o.w = pk2(s[6 * 33] * scale, s[7 * 33] * scale);
;         *(u32x4*)(WT + (drow0 + n) * ldk + k0 + 8 * c) = o; }
	ds_write2_b32 v5, v33, v35 offset1:66
	ds_write2_b32 v5, v43, v62 offset0:132 offset1:198
	ds_write2_b32 v9, v63, v64 offset0:8 offset1:74
	ds_write2_b32 v9, v65, v66 offset0:140 offset1:206
	ds_write2_b32 v36, v67, v68 offset0:16 offset1:82
	ds_write2_b32 v36, v69, v70 offset0:148 offset1:214
	ds_write2_b32 v37, v71, v72 offset0:24 offset1:90
	ds_write2_b32 v37, v73, v74 offset0:156 offset1:222
	ds_write2_b32 v38, v75, v76 offset0:32 offset1:98
	ds_write2_b32 v38, v77, v78 offset0:164 offset1:230
	ds_write2_b32 v39, v79, v80 offset0:40 offset1:106
	ds_write2_b32 v39, v81, v82 offset0:172 offset1:238
	ds_write2_b32 v40, v0, v46 offset0:48 offset1:114
	ds_write2_b32 v40, v47, v48 offset0:180 offset1:246
	ds_write2_b32 v41, v49, v50 offset0:56 offset1:122
	ds_write2_b32 v41, v51, v44 offset0:188 offset1:254
	s_waitcnt lgkmcnt(0)
	ds_read2_b32 v[48:49], v7 offset1:8
	ds_read2_b32 v[52:53], v7 offset0:33 offset1:41
	ds_read2_b32 v[54:55], v7 offset0:66 offset1:74
	ds_read2_b32 v[56:57], v7 offset0:99 offset1:107
	ds_read2_b32 v[58:59], v7 offset0:132 offset1:140
	s_waitcnt lgkmcnt(4)
	v_bfe_u32 v0, v48, 16, 1
	v_add3_u32 v0, v48, v0, s52
	s_waitcnt lgkmcnt(3)
	v_bfe_u32 v33, v52, 16, 1
	v_lshrrev_b32_e32 v0, 16, v0
	v_add3_u32 v33, v52, v33, s52
	ds_read2_b32 v[60:61], v7 offset0:165 offset1:173
	v_and_or_b32 v44, v33, s53, v0
	s_waitcnt lgkmcnt(3)
	v_bfe_u32 v0, v54, 16, 1
	v_add3_u32 v0, v54, v0, s52
	s_waitcnt lgkmcnt(2)
	v_bfe_u32 v33, v56, 16, 1
	ds_read2_b32 v[62:63], v7 offset0:198 offset1:206
	v_lshrrev_b32_e32 v0, 16, v0
	v_add3_u32 v33, v56, v33, s52
	ds_read2_b32 v[64:65], v7 offset0:231 offset1:239
	v_and_or_b32 v45, v33, s53, v0
	s_waitcnt lgkmcnt(3)
	v_bfe_u32 v0, v58, 16, 1
	v_add3_u32 v0, v58, v0, s52
	s_waitcnt lgkmcnt(2)
	v_bfe_u32 v33, v60, 16, 1
	v_lshrrev_b32_e32 v0, 16, v0
	v_add3_u32 v33, v60, v33, s52
	v_and_or_b32 v46, v33, s53, v0
	s_waitcnt lgkmcnt(1)
	v_bfe_u32 v0, v62, 16, 1
	v_add3_u32 v0, v62, v0, s52
	s_waitcnt lgkmcnt(0)
	v_bfe_u32 v33, v64, 16, 1
	v_lshrrev_b32_e32 v0, 16, v0
	v_add3_u32 v33, v64, v33, s52
	s_mov_b32 s27, s25
	v_and_or_b32 v47, v33, s53, v0
	v_or_b32_e32 v0, s28, v2
	v_lshl_add_u64 v[50:51], s[26:27], 1, v[16:17]
	v_lshlrev_b32_e32 v0, 12, v0
	v_lshl_add_u64 v[66:67], v[50:51], 0, v[0:1]
	v_bfe_u32 v0, v49, 16, 1
	v_add3_u32 v0, v49, v0, s52
	v_bfe_u32 v33, v53, 16, 1
	v_lshrrev_b32_e32 v0, 16, v0
	v_add3_u32 v33, v53, v33, s52
	global_store_dwordx4 v[66:67], v[44:47], off
	ds_read2_b32 v[48:49], v7 offset0:16 offset1:24
	s_nop 0
	v_and_or_b32 v44, v33, s53, v0
	v_bfe_u32 v0, v55, 16, 1
	v_add3_u32 v0, v55, v0, s52
	v_bfe_u32 v33, v57, 16, 1
	v_lshrrev_b32_e32 v0, 16, v0
	v_add3_u32 v33, v57, v33, s52
	v_and_or_b32 v45, v33, s53, v0
	v_bfe_u32 v0, v59, 16, 1
	v_add3_u32 v0, v59, v0, s52
	v_bfe_u32 v33, v61, 16, 1
	v_lshrrev_b32_e32 v0, 16, v0
	v_add3_u32 v33, v61, v33, s52
	v_and_or_b32 v46, v33, s53, v0
	v_bfe_u32 v0, v63, 16, 1
	v_add3_u32 v0, v63, v0, s52
	v_bfe_u32 v33, v65, 16, 1
	v_lshrrev_b32_e32 v0, 16, v0
	v_add3_u32 v33, v65, v33, s52
	v_and_or_b32 v47, v33, s53, v0
	v_or_b32_e32 v0, s28, v4
	v_lshlrev_b32_e32 v0, 12, v0
	v_lshl_add_u64 v[52:53], v[50:51], 0, v[0:1]
	global_store_dwordx4 v[52:53], v[44:47], off
	ds_read2_b32 v[52:53], v7 offset0:49 offset1:57
	ds_read2_b32 v[54:55], v7 offset0:82 offset1:90
	ds_read2_b32 v[56:57], v7 offset0:115 offset1:123
	s_waitcnt lgkmcnt(3)
	v_bfe_u32 v0, v48, 16, 1
	v_add3_u32 v0, v48, v0, s52
	s_waitcnt lgkmcnt(2)
	v_bfe_u32 v33, v52, 16, 1
	ds_read2_b32 v[58:59], v7 offset0:148 offset1:156
	v_lshrrev_b32_e32 v0, 16, v0
	v_add3_u32 v33, v52, v33, s52
	ds_read2_b32 v[60:61], v7 offset0:181 offset1:189
	v_and_or_b32 v44, v33, s53, v0
	s_waitcnt lgkmcnt(3)
	v_bfe_u32 v0, v54, 16, 1
	v_add3_u32 v0, v54, v0, s52
	s_waitcnt lgkmcnt(2)
	v_bfe_u32 v33, v56, 16, 1
	ds_read2_b32 v[62:63], v7 offset0:214 offset1:222
	v_lshrrev_b32_e32 v0, 16, v0
	v_add3_u32 v33, v56, v33, s52
	ds_read2_b32 v[64:65], v7 offset0:247 offset1:255
	v_and_or_b32 v45, v33, s53, v0
	s_waitcnt lgkmcnt(3)
	v_bfe_u32 v0, v58, 16, 1
	v_add3_u32 v0, v58, v0, s52
	s_waitcnt lgkmcnt(2)
	v_bfe_u32 v33, v60, 16, 1
	v_lshrrev_b32_e32 v0, 16, v0
	v_add3_u32 v33, v60, v33, s52
	v_and_or_b32 v46, v33, s53, v0
	s_waitcnt lgkmcnt(1)
	v_bfe_u32 v0, v62, 16, 1
	v_add3_u32 v0, v62, v0, s52
	s_waitcnt lgkmcnt(0)
	v_bfe_u32 v33, v64, 16, 1
	v_lshrrev_b32_e32 v0, 16, v0
	v_add3_u32 v33, v64, v33, s52
	v_and_or_b32 v47, v33, s53, v0
	v_or_b32_e32 v0, s28, v6
	v_lshlrev_b32_e32 v0, 12, v0
	v_lshl_add_u64 v[66:67], v[50:51], 0, v[0:1]
	v_bfe_u32 v0, v49, 16, 1
	v_add3_u32 v0, v49, v0, s52
	v_bfe_u32 v33, v53, 16, 1
	v_lshrrev_b32_e32 v0, 16, v0
	v_add3_u32 v33, v53, v33, s52
	global_store_dwordx4 v[66:67], v[44:47], off
	s_nop 1
	v_and_or_b32 v44, v33, s53, v0
	v_bfe_u32 v0, v55, 16, 1
	v_add3_u32 v0, v55, v0, s52
	v_bfe_u32 v33, v57, 16, 1
	v_lshrrev_b32_e32 v0, 16, v0
	v_add3_u32 v33, v57, v33, s52
	v_and_or_b32 v45, v33, s53, v0
	v_bfe_u32 v0, v59, 16, 1
	v_add3_u32 v0, v59, v0, s52
	v_bfe_u32 v33, v61, 16, 1
	v_lshrrev_b32_e32 v0, 16, v0
	v_add3_u32 v33, v61, v33, s52
	v_and_or_b32 v46, v33, s53, v0
	v_bfe_u32 v0, v63, 16, 1
	v_add3_u32 v0, v63, v0, s52
	v_bfe_u32 v33, v65, 16, 1
	v_lshrrev_b32_e32 v0, 16, v0
	v_add3_u32 v33, v65, v33, s52
	v_and_or_b32 v47, v33, s53, v0
	v_or_b32_e32 v0, s28, v8
	v_lshlrev_b32_e32 v0, 12, v0
	v_lshl_add_u64 v[48:49], v[50:51], 0, v[0:1]
	global_store_dwordx4 v[48:49], v[44:47], off
	s_waitcnt lgkmcnt(0)

; #define LAS __attribute__((address_space(3)))
; __device__ __forceinline__ void tr_item(const float* W, int ldw, int k0, int n0, bf16* WT, size_t drow0, int ldk, float scale, LAS float* scr, int lane) {
;     float wv[32];
; #pragma unroll
;     for (int i = 0; i < 32; ++i) wv[i] = W[(size_t)(k0 + 2 * i + (lane >> 5)) * ldw + n0 + (lane & 31)];
; #pragma unroll
;     for (int i = 0; i < 32; ++i) scr[(2 * i + (lane >> 5)) * 33 + (lane & 31)] = wv[i];
; __device__ __forceinline__ void p0_prologue(const P0Args& A, LAS unsigned char* lds, int gw, int NGW, int wave, int lane) {
;     ...
;         if (r < I_DN) { const int nb = D / 32, k0 = 64 * (r / nb), n0 = 32 * (r % nb); tr_item(A.w_down, D, k0, n0, A.Wdn, n0, FFN, 1.f, scr, lane); continue; } r -= I_DN;
.LBB0_35:
	s_andn2_b64 vcc, exec, s[26:27]
	s_cbranch_vccnz .LBB0_37
	s_and_b32 s24, s57, 0x7fc0
	s_add_i32 s26, s24, 0xffffb800
	s_and_b32 s28, s3, 0x7e0
	v_or_b32_e32 v0, s26, v3
	s_lshl_b32 s24, s28, 2
	v_or_b32_e32 v48, 2, v0
	v_mov_b32_e32 v49, v1
	v_or_b32_e32 v50, 4, v0
	v_mov_b32_e32 v51, v1
	v_or_b32_e32 v52, 6, v0
	v_mov_b32_e32 v53, v1
	v_or_b32_e32 v54, 8, v0
	v_mov_b32_e32 v55, v1
	v_or_b32_e32 v56, 10, v0
	v_mov_b32_e32 v57, v1
	v_or_b32_e32 v58, 12, v0
	v_mov_b32_e32 v59, v1
	v_lshl_add_u64 v[44:45], v[18:19], 0, s[24:25]
	v_lshlrev_b64 v[46:47], 13, v[0:1]
	v_lshlrev_b64 v[48:49], 13, v[48:49]
	v_lshlrev_b64 v[50:51], 13, v[50:51]
	v_lshlrev_b64 v[52:53], 13, v[52:53]
	v_lshlrev_b64 v[54:55], 13, v[54:55]
	v_lshlrev_b64 v[56:57], 13, v[56:57]
	v_lshlrev_b64 v[58:59], 13, v[58:59]
	v_or_b32_e32 v60, 14, v0
	v_mov_b32_e32 v61, v1
	v_lshl_add_u64 v[46:47], v[44:45], 0, v[46:47]
	v_lshl_add_u64 v[48:49], v[44:45], 0, v[48:49]
	v_lshl_add_u64 v[50:51], v[44:45], 0, v[50:51]
	v_lshl_add_u64 v[52:53], v[44:45], 0, v[52:53]
	v_lshl_add_u64 v[54:55], v[44:45], 0, v[54:55]
	v_lshl_add_u64 v[56:57], v[44:45], 0, v[56:57]
	v_lshl_add_u64 v[58:59], v[44:45], 0, v[58:59]
	v_lshlrev_b64 v[60:61], 13, v[60:61]
	v_lshl_add_u64 v[60:61], v[44:45], 0, v[60:61]
	flat_load_dword v33, v[46:47] nt
	flat_load_dword v35, v[48:49] nt
	flat_load_dword v43, v[50:51] nt
	flat_load_dword v62, v[52:53] nt
	flat_load_dword v63, v[54:55] nt
	flat_load_dword v64, v[56:57] nt
	flat_load_dword v65, v[58:59] nt
	flat_load_dword v66, v[60:61] nt
	v_or_b32_e32 v46, 16, v0
	v_mov_b32_e32 v47, v1
	v_or_b32_e32 v48, 18, v0
	v_mov_b32_e32 v49, v1
	v_or_b32_e32 v50, 20, v0
	v_mov_b32_e32 v51, v1
	v_or_b32_e32 v52, 22, v0
	v_mov_b32_e32 v53, v1
	v_or_b32_e32 v54, 24, v0
	v_mov_b32_e32 v55, v1
	v_or_b32_e32 v56, 26, v0
	v_mov_b32_e32 v57, v1
	v_or_b32_e32 v58, 28, v0
	v_mov_b32_e32 v59, v1
	v_lshlrev_b64 v[46:47], 13, v[46:47]
	v_lshlrev_b64 v[48:49], 13, v[48:49]
	v_lshlrev_b64 v[50:51], 13, v[50:51]
	v_lshlrev_b64 v[52:53], 13, v[52:53]
	v_lshlrev_b64 v[54:55], 13, v[54:55]
	v_lshlrev_b64 v[56:57], 13, v[56:57]
	v_lshlrev_b64 v[58:59], 13, v[58:59]
	v_or_b32_e32 v60, 30, v0
	v_mov_b32_e32 v61, v1
	v_lshl_add_u64 v[46:47], v[44:45], 0, v[46:47]
	v_lshl_add_u64 v[48:49], v[44:45], 0, v[48:49]
	v_lshl_add_u64 v[50:51], v[44:45], 0, v[50:51]
	v_lshl_add_u64 v[52:53], v[44:45], 0, v[52:53]
	v_lshl_add_u64 v[54:55], v[44:45], 0, v[54:55]
	v_lshl_add_u64 v[56:57], v[44:45], 0, v[56:57]
	v_lshl_add_u64 v[58:59], v[44:45], 0, v[58:59]
	v_lshlrev_b64 v[60:61], 13, v[60:61]
	v_lshl_add_u64 v[60:61], v[44:45], 0, v[60:61]
	flat_load_dword v67, v[46:47] nt
	flat_load_dword v68, v[48:49] nt
	flat_load_dword v69, v[50:51] nt
	flat_load_dword v70, v[52:53] nt
	flat_load_dword v71, v[54:55] nt
	flat_load_dword v72, v[56:57] nt
	flat_load_dword v73, v[58:59] nt
	flat_load_dword v74, v[60:61] nt
	v_or_b32_e32 v46, 32, v0
	v_mov_b32_e32 v47, v1
	v_or_b32_e32 v48, 34, v0
	v_mov_b32_e32 v49, v1
	v_or_b32_e32 v50, 36, v0
	v_mov_b32_e32 v51, v1
	v_or_b32_e32 v52, 38, v0
	v_mov_b32_e32 v53, v1
	v_or_b32_e32 v54, 40, v0
	v_mov_b32_e32 v55, v1
	v_or_b32_e32 v56, 42, v0
	v_mov_b32_e32 v57, v1
	v_or_b32_e32 v58, 44, v0
	v_mov_b32_e32 v59, v1
	v_lshlrev_b64 v[46:47], 13, v[46:47]
	v_lshlrev_b64 v[48:49], 13, v[48:49]
	v_lshlrev_b64 v[50:51], 13, v[50:51]
	v_lshlrev_b64 v[52:53], 13, v[52:53]
	v_lshlrev_b64 v[54:55], 13, v[54:55]
	v_lshlrev_b64 v[56:57], 13, v[56:57]
	v_lshlrev_b64 v[58:59], 13, v[58:59]
	v_or_b32_e32 v60, 46, v0
	v_mov_b32_e32 v61, v1
	v_lshl_add_u64 v[46:47], v[44:45], 0, v[46:47]
	v_lshl_add_u64 v[48:49], v[44:45], 0, v[48:49]
	v_lshl_add_u64 v[50:51], v[44:45], 0, v[50:51]
	v_lshl_add_u64 v[52:53], v[44:45], 0, v[52:53]
	v_lshl_add_u64 v[54:55], v[44:45], 0, v[54:55]
	v_lshl_add_u64 v[56:57], v[44:45], 0, v[56:57]
	v_lshl_add_u64 v[58:59], v[44:45], 0, v[58:59]
	v_lshlrev_b64 v[60:61], 13, v[60:61]
	v_lshl_add_u64 v[60:61], v[44:45], 0, v[60:61]
	flat_load_dword v75, v[46:47] nt
	flat_load_dword v76, v[48:49] nt
	flat_load_dword v77, v[50:51] nt
	flat_load_dword v78, v[52:53] nt
	flat_load_dword v79, v[54:55] nt
	flat_load_dword v80, v[56:57] nt
	flat_load_dword v81, v[58:59] nt
	flat_load_dword v82, v[60:61] nt
	v_or_b32_e32 v46, 48, v0
	v_mov_b32_e32 v47, v1
	v_or_b32_e32 v48, 50, v0
	v_mov_b32_e32 v49, v1
	v_or_b32_e32 v50, 52, v0
	v_mov_b32_e32 v51, v1
	v_or_b32_e32 v52, 54, v0
	v_mov_b32_e32 v53, v1
	v_or_b32_e32 v54, 56, v0
	v_mov_b32_e32 v55, v1
	v_or_b32_e32 v56, 58, v0
	v_mov_b32_e32 v57, v1
	v_or_b32_e32 v58, 60, v0
	v_mov_b32_e32 v59, v1
	v_or_b32_e32 v0, 62, v0
	v_lshlrev_b64 v[46:47], 13, v[46:47]
	v_lshlrev_b64 v[48:49], 13, v[48:49]
	v_lshlrev_b64 v[50:51], 13, v[50:51]
	v_lshlrev_b64 v[52:53], 13, v[52:53]
	v_lshlrev_b64 v[54:55], 13, v[54:55]
	v_lshlrev_b64 v[56:57], 13, v[56:57]
	v_lshlrev_b64 v[58:59], 13, v[58:59]
	v_lshlrev_b64 v[60:61], 13, v[0:1]
	v_lshl_add_u64 v[46:47], v[44:45], 0, v[46:47]
	v_lshl_add_u64 v[48:49], v[44:45], 0, v[48:49]
	v_lshl_add_u64 v[50:51], v[44:45], 0, v[50:51]
	v_lshl_add_u64 v[52:53], v[44:45], 0, v[52:53]
	v_lshl_add_u64 v[54:55], v[44:45], 0, v[54:55]
	v_lshl_add_u64 v[56:57], v[44:45], 0, v[56:57]
	v_lshl_add_u64 v[58:59], v[44:45], 0, v[58:59]
	v_lshl_add_u64 v[44:45], v[44:45], 0, v[60:61]
	flat_load_dword v0, v[46:47] nt
	s_nop 0
	flat_load_dword v46, v[48:49] nt
	flat_load_dword v47, v[50:51] nt
	s_nop 0
	flat_load_dword v48, v[52:53] nt
	flat_load_dword v49, v[54:55] nt
	flat_load_dword v50, v[56:57] nt
	flat_load_dword v51, v[58:59] nt
	s_nop 0
	flat_load_dword v44, v[44:45] nt
	s_waitcnt vmcnt(0) lgkmcnt(0)
; #define LAS __attribute__((address_space(3)))
; __device__ __forceinline__ unsigned pk2(float lo, float hi) { return f2bf(lo) | (f2bf(hi) << 16); }
; __device__ __forceinline__ void tr_item(const float* W, int ldw, int k0, int n0, bf16* WT, size_t drow0, int ldk, float scale, LAS float* scr, int lane) {
;     ...
;     for (int i = 0; i < 32; ++i) scr[(2 * i + (lane >> 5)) * 33 + (lane & 31)] = wv[i];
;     asm volatile("s_waitcnt lgkmcnt(0)" ::: "memory");
;     const int c = lane & 7;
; #pragma unroll
;     for (int j = 0; j < 4; ++j) { const int n = (lane >> 3) + 8 * j; const LAS float* s = scr + (8 * c) * 33 + n;
;         u32x4 o; o.x = pk2(s[0 * 33] * scale, s[1 * 33] * scale); o.y = pk2(s[2 * 33] * scale, s[3 * 33] * scale); o.z = pk2(s[4 * 33] * scale, s[5 * 33] * scale); o.w = pk2(s[6 * 33] * scale, s[7 * 33] * scale);
;         *(u32x4*)(WT + (drow0 + n) * ldk + k0 + 8 * c) = o; }
	ds_write2_b32 v5, v33, v35 offset1:66
	ds_write2_b32 v5, v43, v62 offset0:132 offset1:198
	ds_write2_b32 v9, v63, v64 offset0:8 offset1:74
	ds_write2_b32 v9, v65, v66 offset0:140 offset1:206
	ds_write2_b32 v36, v67, v68 offset0:16 offset1:82
	ds_write2_b32 v36, v69, v70 offset0:148 offset1:214
	ds_write2_b32 v37, v71, v72 offset0:24 offset1:90
	ds_write2_b32 v37, v73, v74 offset0:156 offset1:222
	ds_write2_b32 v38, v75, v76 offset0:32 offset1:98
	ds_write2_b32 v38, v77, v78 offset0:164 offset1:230
	ds_write2_b32 v39, v79, v80 offset0:40 offset1:106
	ds_write2_b32 v39, v81, v82 offset0:172 offset1:238
	ds_write2_b32 v40, v0, v46 offset0:48 offset1:114
	ds_write2_b32 v40, v47, v48 offset0:180 offset1:246
	ds_write2_b32 v41, v49, v50 offset0:56 offset1:122
	ds_write2_b32 v41, v51, v44 offset0:188 offset1:254
	s_waitcnt lgkmcnt(0)
	ds_read2_b32 v[48:49], v7 offset1:8
	ds_read2_b32 v[52:53], v7 offset0:33 offset1:41
	ds_read2_b32 v[54:55], v7 offset0:66 offset1:74
	ds_read2_b32 v[56:57], v7 offset0:99 offset1:107
	ds_read2_b32 v[58:59], v7 offset0:132 offset1:140
	s_waitcnt lgkmcnt(4)
	v_bfe_u32 v0, v48, 16, 1
	v_add3_u32 v0, v48, v0, s52
	s_waitcnt lgkmcnt(3)
	v_bfe_u32 v33, v52, 16, 1
	v_lshrrev_b32_e32 v0, 16, v0
	v_add3_u32 v33, v52, v33, s52
	ds_read2_b32 v[60:61], v7 offset0:165 offset1:173
	v_and_or_b32 v44, v33, s53, v0
	s_waitcnt lgkmcnt(3)
	v_bfe_u32 v0, v54, 16, 1
	v_add3_u32 v0, v54, v0, s52
	s_waitcnt lgkmcnt(2)
	v_bfe_u32 v33, v56, 16, 1
	ds_read2_b32 v[62:63], v7 offset0:198 offset1:206
	v_lshrrev_b32_e32 v0, 16, v0
	v_add3_u32 v33, v56, v33, s52
	ds_read2_b32 v[64:65], v7 offset0:231 offset1:239
	v_and_or_b32 v45, v33, s53, v0
	s_waitcnt lgkmcnt(3)
	v_bfe_u32 v0, v58, 16, 1
	v_add3_u32 v0, v58, v0, s52
	s_waitcnt lgkmcnt(2)
	v_bfe_u32 v33, v60, 16, 1
	v_lshrrev_b32_e32 v0, 16, v0
	v_add3_u32 v33, v60, v33, s52
	v_and_or_b32 v46, v33, s53, v0
	s_waitcnt lgkmcnt(1)
	v_bfe_u32 v0, v62, 16, 1
	v_add3_u32 v0, v62, v0, s52
	s_waitcnt lgkmcnt(0)
	v_bfe_u32 v33, v64, 16, 1
	v_lshrrev_b32_e32 v0, 16, v0
	v_add3_u32 v33, v64, v33, s52
	v_and_or_b32 v47, v33, s53, v0
	v_or_b32_e32 v0, s28, v2
	s_mov_b32 s27, s25
	v_mul_u32_u24_e32 v0, 0x1600, v0
	v_lshl_add_u64 v[50:51], s[26:27], 1, v[20:21]
	v_lshlrev_b32_e32 v0, 1, v0
	v_lshl_add_u64 v[66:67], v[50:51], 0, v[0:1]
	v_bfe_u32 v0, v49, 16, 1
	v_add3_u32 v0, v49, v0, s52
	v_bfe_u32 v33, v53, 16, 1
	v_lshrrev_b32_e32 v0, 16, v0
	v_add3_u32 v33, v53, v33, s52
	global_store_dwordx4 v[66:67], v[44:47], off
	ds_read2_b32 v[48:49], v7 offset0:16 offset1:24
	s_nop 0
	v_and_or_b32 v44, v33, s53, v0
	v_bfe_u32 v0, v55, 16, 1
	v_add3_u32 v0, v55, v0, s52
	v_bfe_u32 v33, v57, 16, 1
	v_lshrrev_b32_e32 v0, 16, v0
	v_add3_u32 v33, v57, v33, s52
	v_and_or_b32 v45, v33, s53, v0
	v_bfe_u32 v0, v59, 16, 1
	v_add3_u32 v0, v59, v0, s52
	v_bfe_u32 v33, v61, 16, 1
	v_lshrrev_b32_e32 v0, 16, v0
	v_add3_u32 v33, v61, v33, s52
	v_and_or_b32 v46, v33, s53, v0
	v_bfe_u32 v0, v63, 16, 1
	v_add3_u32 v0, v63, v0, s52
	v_bfe_u32 v33, v65, 16, 1
	v_lshrrev_b32_e32 v0, 16, v0
	v_add3_u32 v33, v65, v33, s52
	v_and_or_b32 v47, v33, s53, v0
	v_or_b32_e32 v0, s28, v4
	v_mul_u32_u24_e32 v0, 0x1600, v0
	v_lshlrev_b32_e32 v0, 1, v0
	v_lshl_add_u64 v[52:53], v[50:51], 0, v[0:1]
	global_store_dwordx4 v[52:53], v[44:47], off
	ds_read2_b32 v[52:53], v7 offset0:49 offset1:57
	ds_read2_b32 v[54:55], v7 offset0:82 offset1:90
	ds_read2_b32 v[56:57], v7 offset0:115 offset1:123
	s_waitcnt lgkmcnt(3)
	v_bfe_u32 v0, v48, 16, 1
	v_add3_u32 v0, v48, v0, s52
	s_waitcnt lgkmcnt(2)
	v_bfe_u32 v33, v52, 16, 1
	ds_read2_b32 v[58:59], v7 offset0:148 offset1:156
	v_lshrrev_b32_e32 v0, 16, v0
	v_add3_u32 v33, v52, v33, s52
	ds_read2_b32 v[60:61], v7 offset0:181 offset1:189
	v_and_or_b32 v44, v33, s53, v0
	s_waitcnt lgkmcnt(3)
	v_bfe_u32 v0, v54, 16, 1
	v_add3_u32 v0, v54, v0, s52
	s_waitcnt lgkmcnt(2)
	v_bfe_u32 v33, v56, 16, 1
	ds_read2_b32 v[62:63], v7 offset0:214 offset1:222
	v_lshrrev_b32_e32 v0, 16, v0
	v_add3_u32 v33, v56, v33, s52
	ds_read2_b32 v[64:65], v7 offset0:247 offset1:255
	v_and_or_b32 v45, v33, s53, v0
	s_waitcnt lgkmcnt(3)
	v_bfe_u32 v0, v58, 16, 1
	v_add3_u32 v0, v58, v0, s52
	s_waitcnt lgkmcnt(2)
	v_bfe_u32 v33, v60, 16, 1
	v_lshrrev_b32_e32 v0, 16, v0
	v_add3_u32 v33, v60, v33, s52
	v_and_or_b32 v46, v33, s53, v0
	s_waitcnt lgkmcnt(1)
	v_bfe_u32 v0, v62, 16, 1
	v_add3_u32 v0, v62, v0, s52
	s_waitcnt lgkmcnt(0)
	v_bfe_u32 v33, v64, 16, 1
	v_lshrrev_b32_e32 v0, 16, v0
	v_add3_u32 v33, v64, v33, s52
	v_and_or_b32 v47, v33, s53, v0
	v_or_b32_e32 v0, s28, v6
	v_mul_u32_u24_e32 v0, 0x1600, v0
	v_lshlrev_b32_e32 v0, 1, v0
	v_lshl_add_u64 v[66:67], v[50:51], 0, v[0:1]
	v_bfe_u32 v0, v49, 16, 1
	v_add3_u32 v0, v49, v0, s52
	v_bfe_u32 v33, v53, 16, 1
	v_lshrrev_b32_e32 v0, 16, v0
	v_add3_u32 v33, v53, v33, s52
	global_store_dwordx4 v[66:67], v[44:47], off
	s_nop 1
	v_and_or_b32 v44, v33, s53, v0
	v_bfe_u32 v0, v55, 16, 1
	v_add3_u32 v0, v55, v0, s52
	v_bfe_u32 v33, v57, 16, 1
	v_lshrrev_b32_e32 v0, 16, v0
	v_add3_u32 v33, v57, v33, s52
	v_and_or_b32 v45, v33, s53, v0
	v_bfe_u32 v0, v59, 16, 1
	v_add3_u32 v0, v59, v0, s52
	v_bfe_u32 v33, v61, 16, 1
	v_lshrrev_b32_e32 v0, 16, v0
	v_add3_u32 v33, v61, v33, s52
	v_and_or_b32 v46, v33, s53, v0
	v_bfe_u32 v0, v63, 16, 1
	v_add3_u32 v0, v63, v0, s52
	v_bfe_u32 v33, v65, 16, 1
	v_lshrrev_b32_e32 v0, 16, v0
	v_add3_u32 v33, v65, v33, s52
	v_and_or_b32 v47, v33, s53, v0
	v_or_b32_e32 v0, s28, v8
	v_mul_u32_u24_e32 v0, 0x1600, v0
	v_lshlrev_b32_e32 v0, 1, v0
	v_lshl_add_u64 v[48:49], v[50:51], 0, v[0:1]
	global_store_dwordx4 v[48:49], v[44:47], off
	s_waitcnt lgkmcnt(0)

; #define LAS __attribute__((address_space(3)))
; __device__ __forceinline__ void tr_item(const float* W, int ldw, int k0, int n0, bf16* WT, size_t drow0, int ldk, float scale, LAS float* scr, int lane) {
;     float wv[32];
; #pragma unroll
;     for (int i = 0; i < 32; ++i) wv[i] = W[(size_t)(k0 + 2 * i + (lane >> 5)) * ldw + n0 + (lane & 31)];
; __device__ __forceinline__ void p0_prologue(const P0Args& A, LAS unsigned char* lds, int gw, int NGW, int wave, int lane) {
;     ...
;         if (r < 2 * I_G) { const int up = r >= I_G; if (up) r -= I_G; const int nb = FFN / 32, k0 = 64 * (r / nb), n0 = 32 * (r % nb);
;             tr_item(up ? A.w_up : A.w_gate, FFN, k0, n0, A.Wgu, (size_t)(n0 / 128) * 256 + (n0 % 128) + (up ? 128 : 0), D, 1.f, scr, lane); continue; } r -= 2 * I_G;
.LBB0_38:
	s_andn2_b64 vcc, exec, s[26:27]
	s_cbranch_vccnz .LBB0_40
	s_cmpk_gt_u32 s57, 0x31ff
	s_cselect_b32 s24, s54, 0xffffe400
	s_cselect_b32 s27, s10, s8
	s_cselect_b32 s36, s11, s9
	s_cselect_b32 s26, 0x80, 0
	s_add_i32 s24, s24, s57
	s_mul_hi_u32 s37, s24, 0xba2e8ba3
	s_lshr_b32 s28, s37, 7
	s_mul_i32 s29, s28, 0xb0
	s_sub_i32 s29, s24, s29
	s_lshl_b32 s24, s29, 5
	s_lshl_b32 s29, s29, 6
	s_and_b32 s29, s29, 0x3f00
	s_and_b32 s58, s24, 0x60
	s_or_b32 s29, s29, s58
	s_or_b32 s26, s26, s29
	v_lshl_or_b32 v0, s28, 6, v3
	s_lshl_b64 s[28:29], s[24:25], 2
	s_add_u32 s28, s27, s28
	s_addc_u32 s29, s36, s29
	v_mov_b32_e32 v35, v1
	v_lshl_add_u64 v[44:45], s[28:29], 0, v[34:35]
	v_or_b32_e32 v33, 2, v0
	v_mad_u64_u32 v[48:49], s[28:29], v33, s55, v[44:45]
	v_or_b32_e32 v33, 4, v0
	v_mad_u64_u32 v[50:51], s[28:29], v33, s55, v[44:45]
	v_or_b32_e32 v33, 6, v0
	v_mad_u64_u32 v[52:53], s[28:29], v33, s55, v[44:45]
	v_or_b32_e32 v33, 8, v0
	v_mad_u64_u32 v[54:55], s[28:29], v33, s55, v[44:45]
	v_or_b32_e32 v33, 10, v0
	v_mad_u64_u32 v[56:57], s[28:29], v33, s55, v[44:45]
	v_or_b32_e32 v33, 12, v0
	v_mad_u64_u32 v[58:59], s[28:29], v33, s55, v[44:45]
	v_or_b32_e32 v33, 14, v0
	v_mad_u64_u32 v[46:47], s[28:29], v0, s55, v[44:45]
	v_mad_u64_u32 v[60:61], s[28:29], v33, s55, v[44:45]
	flat_load_dword v33, v[46:47] nt
	flat_load_dword v35, v[48:49] nt
	flat_load_dword v43, v[50:51] nt
	flat_load_dword v62, v[52:53] nt
	flat_load_dword v63, v[54:55] nt
	flat_load_dword v64, v[56:57] nt
	flat_load_dword v65, v[58:59] nt
	flat_load_dword v66, v[60:61] nt
	v_or_b32_e32 v46, 16, v0
	v_or_b32_e32 v48, 18, v0
	v_or_b32_e32 v50, 20, v0
	v_or_b32_e32 v52, 22, v0
	v_or_b32_e32 v54, 24, v0
	v_or_b32_e32 v56, 26, v0
	v_or_b32_e32 v58, 28, v0
	v_or_b32_e32 v60, 30, v0
	v_mad_u64_u32 v[46:47], s[28:29], v46, s55, v[44:45]
	v_mad_u64_u32 v[48:49], s[28:29], v48, s55, v[44:45]
	v_mad_u64_u32 v[50:51], s[28:29], v50, s55, v[44:45]
	v_mad_u64_u32 v[52:53], s[28:29], v52, s55, v[44:45]
	v_mad_u64_u32 v[54:55], s[28:29], v54, s55, v[44:45]
	v_mad_u64_u32 v[56:57], s[28:29], v56, s55, v[44:45]
	v_mad_u64_u32 v[58:59], s[28:29], v58, s55, v[44:45]
	v_mad_u64_u32 v[60:61], s[28:29], v60, s55, v[44:45]
	flat_load_dword v67, v[46:47] nt
	flat_load_dword v68, v[48:49] nt
	flat_load_dword v69, v[50:51] nt
	flat_load_dword v70, v[52:53] nt
	flat_load_dword v71, v[54:55] nt
	flat_load_dword v72, v[56:57] nt
	flat_load_dword v73, v[58:59] nt
	flat_load_dword v74, v[60:61] nt
	v_or_b32_e32 v46, 32, v0
	v_or_b32_e32 v48, 34, v0
	v_or_b32_e32 v50, 36, v0
	v_or_b32_e32 v52, 38, v0
	v_or_b32_e32 v54, 40, v0
	v_or_b32_e32 v56, 42, v0
	v_or_b32_e32 v58, 44, v0
	v_or_b32_e32 v60, 46, v0
	v_mad_u64_u32 v[46:47], s[28:29], v46, s55, v[44:45]
	v_mad_u64_u32 v[48:49], s[28:29], v48, s55, v[44:45]
	v_mad_u64_u32 v[50:51], s[28:29], v50, s55, v[44:45]
	v_mad_u64_u32 v[52:53], s[28:29], v52, s55, v[44:45]
	v_mad_u64_u32 v[54:55], s[28:29], v54, s55, v[44:45]
	v_mad_u64_u32 v[56:57], s[28:29], v56, s55, v[44:45]
	v_mad_u64_u32 v[58:59], s[28:29], v58, s55, v[44:45]
	v_mad_u64_u32 v[60:61], s[28:29], v60, s55, v[44:45]
	flat_load_dword v75, v[46:47] nt
	flat_load_dword v76, v[48:49] nt
	flat_load_dword v77, v[50:51] nt
	flat_load_dword v78, v[52:53] nt
	flat_load_dword v79, v[54:55] nt
	flat_load_dword v80, v[56:57] nt
	flat_load_dword v81, v[58:59] nt
	s_nop 0
	flat_load_dword v60, v[60:61] nt
	v_or_b32_e32 v46, 48, v0
	v_or_b32_e32 v48, 50, v0
	v_or_b32_e32 v50, 52, v0
	v_or_b32_e32 v52, 54, v0
	v_or_b32_e32 v54, 56, v0
	v_or_b32_e32 v56, 58, v0
	v_or_b32_e32 v58, 60, v0
	v_or_b32_e32 v0, 62, v0
	v_mad_u64_u32 v[46:47], s[28:29], v46, s55, v[44:45]
	v_mad_u64_u32 v[48:49], s[28:29], v48, s55, v[44:45]
	v_mad_u64_u32 v[50:51], s[28:29], v50, s55, v[44:45]
	v_mad_u64_u32 v[52:53], s[28:29], v52, s55, v[44:45]
	v_mad_u64_u32 v[54:55], s[28:29], v54, s55, v[44:45]
	v_mad_u64_u32 v[56:57], s[28:29], v56, s55, v[44:45]
	v_mad_u64_u32 v[58:59], s[28:29], v58, s55, v[44:45]
	v_mad_u64_u32 v[44:45], s[28:29], v0, s55, v[44:45]
	flat_load_dword v0, v[46:47] nt
	s_nop 0
	flat_load_dword v46, v[48:49] nt
	flat_load_dword v47, v[50:51] nt
	s_nop 0
	flat_load_dword v48, v[52:53] nt
	flat_load_dword v49, v[54:55] nt
	flat_load_dword v50, v[56:57] nt
	flat_load_dword v51, v[58:59] nt
	s_nop 0
	flat_load_dword v44, v[44:45] nt
	s_waitcnt vmcnt(0) lgkmcnt(0)
	ds_write2_b32 v5, v33, v35 offset1:66
	ds_write2_b32 v5, v43, v62 offset0:132 offset1:198
	ds_write2_b32 v9, v63, v64 offset0:8 offset1:74
	ds_write2_b32 v9, v65, v66 offset0:140 offset1:206
	ds_write2_b32 v36, v67, v68 offset0:16 offset1:82
	ds_write2_b32 v36, v69, v70 offset0:148 offset1:214
	ds_write2_b32 v37, v71, v72 offset0:24 offset1:90
	ds_write2_b32 v37, v73, v74 offset0:156 offset1:222
	ds_write2_b32 v38, v75, v76 offset0:32 offset1:98
	ds_write2_b32 v38, v77, v78 offset0:164 offset1:230
	ds_write2_b32 v39, v79, v80 offset0:40 offset1:106
	ds_write2_b32 v39, v81, v60 offset0:172 offset1:238
	ds_write2_b32 v40, v0, v46 offset0:48 offset1:114
	ds_write2_b32 v40, v47, v48 offset0:180 offset1:246
	ds_write2_b32 v41, v49, v50 offset0:56 offset1:122
	ds_write2_b32 v41, v51, v44 offset0:188 offset1:254
	s_waitcnt lgkmcnt(0)
; #define LAS __attribute__((address_space(3)))
; __device__ __forceinline__ unsigned pk2(float lo, float hi) { return f2bf(lo) | (f2bf(hi) << 16); }
; __device__ __forceinline__ void tr_item(const float* W, int ldw, int k0, int n0, bf16* WT, size_t drow0, int ldk, float scale, LAS float* scr, int lane) {
;     ...
;     asm volatile("s_waitcnt lgkmcnt(0)" ::: "memory");
;     const int c = lane & 7;
; #pragma unroll
;     for (int j = 0; j < 4; ++j) { const int n = (lane >> 3) + 8 * j; const LAS float* s = scr + (8 * c) * 33 + n;
;         u32x4 o; o.x = pk2(s[0 * 33] * scale, s[1 * 33] * scale); o.y = pk2(s[2 * 33] * scale, s[3 * 33] * scale); o.z = pk2(s[4 * 33] * scale, s[5 * 33] * scale); o.w = pk2(s[6 * 33] * scale, s[7 * 33] * scale);
;         *(u32x4*)(WT + (drow0 + n) * ldk + k0 + 8 * c) = o; }
	ds_read2_b32 v[48:49], v7 offset1:8
	ds_read2_b32 v[52:53], v7 offset0:33 offset1:41
	ds_read2_b32 v[54:55], v7 offset0:66 offset1:74
	ds_read2_b32 v[56:57], v7 offset0:99 offset1:107
	ds_read2_b32 v[58:59], v7 offset0:132 offset1:140
	s_waitcnt lgkmcnt(4)
	v_bfe_u32 v0, v48, 16, 1
	v_add3_u32 v0, v48, v0, s52
	s_waitcnt lgkmcnt(3)
	v_bfe_u32 v33, v52, 16, 1
	v_lshrrev_b32_e32 v0, 16, v0
	v_add3_u32 v33, v52, v33, s52
	ds_read2_b32 v[60:61], v7 offset0:165 offset1:173
	v_and_or_b32 v44, v33, s53, v0
	s_waitcnt lgkmcnt(3)
	v_bfe_u32 v0, v54, 16, 1
	v_add3_u32 v0, v54, v0, s52
	s_waitcnt lgkmcnt(2)
	v_bfe_u32 v33, v56, 16, 1
	ds_read2_b32 v[62:63], v7 offset0:198 offset1:206
	v_lshrrev_b32_e32 v0, 16, v0
	v_add3_u32 v33, v56, v33, s52
	ds_read2_b32 v[64:65], v7 offset0:231 offset1:239
	v_and_or_b32 v45, v33, s53, v0
	s_waitcnt lgkmcnt(3)
	v_bfe_u32 v0, v58, 16, 1
	v_add3_u32 v0, v58, v0, s52
	s_waitcnt lgkmcnt(2)
	v_bfe_u32 v33, v60, 16, 1
	v_lshrrev_b32_e32 v0, 16, v0
	v_add3_u32 v33, v60, v33, s52
	v_and_or_b32 v46, v33, s53, v0
	s_waitcnt lgkmcnt(1)
	v_bfe_u32 v0, v62, 16, 1
	v_add3_u32 v0, v62, v0, s52
	s_waitcnt lgkmcnt(0)
	v_bfe_u32 v33, v64, 16, 1
	v_lshrrev_b32_e32 v0, 16, v0
	v_add3_u32 v33, v64, v33, s52
	s_and_b32 s24, s37, 0xffffff80
	v_and_or_b32 v47, v33, s53, v0
	v_or_b32_e32 v0, s26, v2
	v_lshl_add_u64 v[50:51], v[22:23], 0, s[24:25]
	v_lshlrev_b32_e32 v0, 12, v0
	v_lshl_add_u64 v[66:67], v[50:51], 0, v[0:1]
	v_bfe_u32 v0, v49, 16, 1
	v_add3_u32 v0, v49, v0, s52
	v_bfe_u32 v33, v53, 16, 1
	v_lshrrev_b32_e32 v0, 16, v0
	v_add3_u32 v33, v53, v33, s52
	global_store_dwordx4 v[66:67], v[44:47], off
	ds_read2_b32 v[48:49], v7 offset0:16 offset1:24
	s_nop 0
	v_and_or_b32 v44, v33, s53, v0
	v_bfe_u32 v0, v55, 16, 1
	v_add3_u32 v0, v55, v0, s52
	v_bfe_u32 v33, v57, 16, 1
	v_lshrrev_b32_e32 v0, 16, v0
	v_add3_u32 v33, v57, v33, s52
	v_and_or_b32 v45, v33, s53, v0
	v_bfe_u32 v0, v59, 16, 1
	v_add3_u32 v0, v59, v0, s52
	v_bfe_u32 v33, v61, 16, 1
	v_lshrrev_b32_e32 v0, 16, v0
	v_add3_u32 v33, v61, v33, s52
	v_and_or_b32 v46, v33, s53, v0
	v_bfe_u32 v0, v63, 16, 1
	v_add3_u32 v0, v63, v0, s52
	v_bfe_u32 v33, v65, 16, 1
	v_lshrrev_b32_e32 v0, 16, v0
	v_add3_u32 v33, v65, v33, s52
	v_and_or_b32 v47, v33, s53, v0
	v_or_b32_e32 v0, s26, v4
	v_lshlrev_b32_e32 v0, 12, v0
	v_lshl_add_u64 v[52:53], v[50:51], 0, v[0:1]
	global_store_dwordx4 v[52:53], v[44:47], off
	ds_read2_b32 v[52:53], v7 offset0:49 offset1:57
	ds_read2_b32 v[54:55], v7 offset0:82 offset1:90
	ds_read2_b32 v[56:57], v7 offset0:115 offset1:123
	s_waitcnt lgkmcnt(3)
	v_bfe_u32 v0, v48, 16, 1
	v_add3_u32 v0, v48, v0, s52
	s_waitcnt lgkmcnt(2)
	v_bfe_u32 v33, v52, 16, 1
	ds_read2_b32 v[58:59], v7 offset0:148 offset1:156
	v_lshrrev_b32_e32 v0, 16, v0
	v_add3_u32 v33, v52, v33, s52
	ds_read2_b32 v[60:61], v7 offset0:181 offset1:189
	v_and_or_b32 v44, v33, s53, v0
	s_waitcnt lgkmcnt(3)
	v_bfe_u32 v0, v54, 16, 1
	v_add3_u32 v0, v54, v0, s52
	s_waitcnt lgkmcnt(2)
	v_bfe_u32 v33, v56, 16, 1
	ds_read2_b32 v[62:63], v7 offset0:214 offset1:222
	v_lshrrev_b32_e32 v0, 16, v0
	v_add3_u32 v33, v56, v33, s52
	ds_read2_b32 v[64:65], v7 offset0:247 offset1:255
	v_and_or_b32 v45, v33, s53, v0
	s_waitcnt lgkmcnt(3)
	v_bfe_u32 v0, v58, 16, 1
	v_add3_u32 v0, v58, v0, s52
	s_waitcnt lgkmcnt(2)
	v_bfe_u32 v33, v60, 16, 1
	v_lshrrev_b32_e32 v0, 16, v0
	v_add3_u32 v33, v60, v33, s52
	v_and_or_b32 v46, v33, s53, v0
	s_waitcnt lgkmcnt(1)
	v_bfe_u32 v0, v62, 16, 1
	v_add3_u32 v0, v62, v0, s52
	s_waitcnt lgkmcnt(0)
	v_bfe_u32 v33, v64, 16, 1
	v_lshrrev_b32_e32 v0, 16, v0
	v_add3_u32 v33, v64, v33, s52
	v_and_or_b32 v47, v33, s53, v0
	v_or_b32_e32 v0, s26, v6
	v_lshlrev_b32_e32 v0, 12, v0
	v_lshl_add_u64 v[66:67], v[50:51], 0, v[0:1]
	v_bfe_u32 v0, v49, 16, 1
	v_add3_u32 v0, v49, v0, s52
	v_bfe_u32 v33, v53, 16, 1
	v_lshrrev_b32_e32 v0, 16, v0
	v_add3_u32 v33, v53, v33, s52
	global_store_dwordx4 v[66:67], v[44:47], off
	s_nop 1
	v_and_or_b32 v44, v33, s53, v0
	v_bfe_u32 v0, v55, 16, 1
	v_add3_u32 v0, v55, v0, s52
	v_bfe_u32 v33, v57, 16, 1
	v_lshrrev_b32_e32 v0, 16, v0
	v_add3_u32 v33, v57, v33, s52
	v_and_or_b32 v45, v33, s53, v0
	v_bfe_u32 v0, v59, 16, 1
	v_add3_u32 v0, v59, v0, s52
	v_bfe_u32 v33, v61, 16, 1
	v_lshrrev_b32_e32 v0, 16, v0
	v_add3_u32 v33, v61, v33, s52
	v_and_or_b32 v46, v33, s53, v0
	v_bfe_u32 v0, v63, 16, 1
	v_add3_u32 v0, v63, v0, s52
	v_bfe_u32 v33, v65, 16, 1
	v_lshrrev_b32_e32 v0, 16, v0
	v_add3_u32 v33, v65, v33, s52
	v_and_or_b32 v47, v33, s53, v0
	v_or_b32_e32 v0, s26, v8
	v_lshlrev_b32_e32 v0, 12, v0
	v_lshl_add_u64 v[48:49], v[50:51], 0, v[0:1]
	global_store_dwordx4 v[48:49], v[44:47], off
	s_waitcnt lgkmcnt(0)

; #define LAS __attribute__((address_space(3)))
; __device__ __forceinline__ void tr_item(const float* W, int ldw, int k0, int n0, bf16* WT, size_t drow0, int ldk, float scale, LAS float* scr, int lane) {
;     float wv[32];
; #pragma unroll
;     for (int i = 0; i < 32; ++i) wv[i] = W[(size_t)(k0 + 2 * i + (lane >> 5)) * ldw + n0 + (lane & 31)];
; #pragma unroll
;     for (int i = 0; i < 32; ++i) scr[(2 * i + (lane >> 5)) * 33 + (lane & 31)] = wv[i];
;     asm volatile("s_waitcnt lgkmcnt(0)" ::: "memory");
; __device__ __forceinline__ void p0_prologue(const P0Args& A, LAS unsigned char* lds, int gw, int NGW, int wave, int lane) {
;     ...
;         if (r < I_OUT) { const int nb = D / 32, k0 = 64 * (r / nb), n0 = 32 * (r % nb); tr_item(A.w_out, D, k0, n0, A.Wout, n0, D, 1.f, scr, lane); continue; } r -= I_OUT;
.LBB0_41:
	s_andn2_b64 vcc, exec, s[26:27]
	s_cbranch_vccnz .LBB0_43
	s_and_b32 s24, s57, 0x1fc0
	s_add_i32 s26, s24, 0xffffec00
	s_and_b32 s28, s3, 0x7e0
	v_or_b32_e32 v0, s26, v3
	s_lshl_b32 s24, s28, 2
	v_or_b32_e32 v48, 2, v0
	v_mov_b32_e32 v49, v1
	v_or_b32_e32 v50, 4, v0
	v_mov_b32_e32 v51, v1
	v_or_b32_e32 v52, 6, v0
	v_mov_b32_e32 v53, v1
	v_or_b32_e32 v54, 8, v0
	v_mov_b32_e32 v55, v1
	v_or_b32_e32 v56, 10, v0
	v_mov_b32_e32 v57, v1
	v_or_b32_e32 v58, 12, v0
	v_mov_b32_e32 v59, v1
	v_lshl_add_u64 v[44:45], v[24:25], 0, s[24:25]
	v_lshlrev_b64 v[46:47], 13, v[0:1]
	v_lshlrev_b64 v[48:49], 13, v[48:49]
	v_lshlrev_b64 v[50:51], 13, v[50:51]
	v_lshlrev_b64 v[52:53], 13, v[52:53]
	v_lshlrev_b64 v[54:55], 13, v[54:55]
	v_lshlrev_b64 v[56:57], 13, v[56:57]
	v_lshlrev_b64 v[58:59], 13, v[58:59]
	v_or_b32_e32 v60, 14, v0
	v_mov_b32_e32 v61, v1
	v_lshl_add_u64 v[46:47], v[44:45], 0, v[46:47]
	v_lshl_add_u64 v[48:49], v[44:45], 0, v[48:49]
	v_lshl_add_u64 v[50:51], v[44:45], 0, v[50:51]
	v_lshl_add_u64 v[52:53], v[44:45], 0, v[52:53]
	v_lshl_add_u64 v[54:55], v[44:45], 0, v[54:55]
	v_lshl_add_u64 v[56:57], v[44:45], 0, v[56:57]
	v_lshl_add_u64 v[58:59], v[44:45], 0, v[58:59]
	v_lshlrev_b64 v[60:61], 13, v[60:61]
	v_lshl_add_u64 v[60:61], v[44:45], 0, v[60:61]
	flat_load_dword v33, v[46:47] nt
	flat_load_dword v35, v[48:49] nt
	flat_load_dword v43, v[50:51] nt
	flat_load_dword v62, v[52:53] nt
	flat_load_dword v63, v[54:55] nt
	flat_load_dword v64, v[56:57] nt
	flat_load_dword v65, v[58:59] nt
	flat_load_dword v66, v[60:61] nt
	v_or_b32_e32 v46, 16, v0
	v_mov_b32_e32 v47, v1
	v_or_b32_e32 v48, 18, v0
	v_mov_b32_e32 v49, v1
	v_or_b32_e32 v50, 20, v0
	v_mov_b32_e32 v51, v1
	v_or_b32_e32 v52, 22, v0
	v_mov_b32_e32 v53, v1
	v_or_b32_e32 v54, 24, v0
	v_mov_b32_e32 v55, v1
	v_or_b32_e32 v56, 26, v0
	v_mov_b32_e32 v57, v1
	v_or_b32_e32 v58, 28, v0
	v_mov_b32_e32 v59, v1
	v_lshlrev_b64 v[46:47], 13, v[46:47]
	v_lshlrev_b64 v[48:49], 13, v[48:49]
	v_lshlrev_b64 v[50:51], 13, v[50:51]
	v_lshlrev_b64 v[52:53], 13, v[52:53]
	v_lshlrev_b64 v[54:55], 13, v[54:55]
	v_lshlrev_b64 v[56:57], 13, v[56:57]
	v_lshlrev_b64 v[58:59], 13, v[58:59]
	v_or_b32_e32 v60, 30, v0
	v_mov_b32_e32 v61, v1
	v_lshl_add_u64 v[46:47], v[44:45], 0, v[46:47]
	v_lshl_add_u64 v[48:49], v[44:45], 0, v[48:49]
	v_lshl_add_u64 v[50:51], v[44:45], 0, v[50:51]
	v_lshl_add_u64 v[52:53], v[44:45], 0, v[52:53]
	v_lshl_add_u64 v[54:55], v[44:45], 0, v[54:55]
	v_lshl_add_u64 v[56:57], v[44:45], 0, v[56:57]
	v_lshl_add_u64 v[58:59], v[44:45], 0, v[58:59]
	v_lshlrev_b64 v[60:61], 13, v[60:61]
	v_lshl_add_u64 v[60:61], v[44:45], 0, v[60:61]
	flat_load_dword v67, v[46:47] nt
	flat_load_dword v68, v[48:49] nt
	flat_load_dword v69, v[50:51] nt
	flat_load_dword v70, v[52:53] nt
	flat_load_dword v71, v[54:55] nt
	flat_load_dword v72, v[56:57] nt
	flat_load_dword v73, v[58:59] nt
	flat_load_dword v74, v[60:61] nt
	v_or_b32_e32 v46, 32, v0
	v_mov_b32_e32 v47, v1
	v_or_b32_e32 v48, 34, v0
	v_mov_b32_e32 v49, v1
	v_or_b32_e32 v50, 36, v0
	v_mov_b32_e32 v51, v1
	v_or_b32_e32 v52, 38, v0
	v_mov_b32_e32 v53, v1
	v_or_b32_e32 v54, 40, v0
	v_mov_b32_e32 v55, v1
	v_or_b32_e32 v56, 42, v0
	v_mov_b32_e32 v57, v1
	v_or_b32_e32 v58, 44, v0
	v_mov_b32_e32 v59, v1
	v_lshlrev_b64 v[46:47], 13, v[46:47]
	v_lshlrev_b64 v[48:49], 13, v[48:49]
	v_lshlrev_b64 v[50:51], 13, v[50:51]
	v_lshlrev_b64 v[52:53], 13, v[52:53]
	v_lshlrev_b64 v[54:55], 13, v[54:55]
	v_lshlrev_b64 v[56:57], 13, v[56:57]
	v_lshlrev_b64 v[58:59], 13, v[58:59]
	v_or_b32_e32 v60, 46, v0
	v_mov_b32_e32 v61, v1
	v_lshl_add_u64 v[46:47], v[44:45], 0, v[46:47]
	v_lshl_add_u64 v[48:49], v[44:45], 0, v[48:49]
	v_lshl_add_u64 v[50:51], v[44:45], 0, v[50:51]
	v_lshl_add_u64 v[52:53], v[44:45], 0, v[52:53]
	v_lshl_add_u64 v[54:55], v[44:45], 0, v[54:55]
	v_lshl_add_u64 v[56:57], v[44:45], 0, v[56:57]
	v_lshl_add_u64 v[58:59], v[44:45], 0, v[58:59]
	v_lshlrev_b64 v[60:61], 13, v[60:61]
	v_lshl_add_u64 v[60:61], v[44:45], 0, v[60:61]
	flat_load_dword v75, v[46:47] nt
	flat_load_dword v76, v[48:49] nt
	flat_load_dword v77, v[50:51] nt
	flat_load_dword v78, v[52:53] nt
	flat_load_dword v79, v[54:55] nt
	flat_load_dword v80, v[56:57] nt
	flat_load_dword v81, v[58:59] nt
	flat_load_dword v82, v[60:61] nt
	v_or_b32_e32 v46, 48, v0
	v_mov_b32_e32 v47, v1
	v_or_b32_e32 v48, 50, v0
	v_mov_b32_e32 v49, v1
	v_or_b32_e32 v50, 52, v0
	v_mov_b32_e32 v51, v1
	v_or_b32_e32 v52, 54, v0
	v_mov_b32_e32 v53, v1
	v_or_b32_e32 v54, 56, v0
	v_mov_b32_e32 v55, v1
	v_or_b32_e32 v56, 58, v0
	v_mov_b32_e32 v57, v1
	v_or_b32_e32 v58, 60, v0
	v_mov_b32_e32 v59, v1
	v_or_b32_e32 v0, 62, v0
	v_lshlrev_b64 v[46:47], 13, v[46:47]
	v_lshlrev_b64 v[48:49], 13, v[48:49]
	v_lshlrev_b64 v[50:51], 13, v[50:51]
	v_lshlrev_b64 v[52:53], 13, v[52:53]
	v_lshlrev_b64 v[54:55], 13, v[54:55]
	v_lshlrev_b64 v[56:57], 13, v[56:57]
	v_lshlrev_b64 v[58:59], 13, v[58:59]
	v_lshlrev_b64 v[60:61], 13, v[0:1]
	v_lshl_add_u64 v[46:47], v[44:45], 0, v[46:47]
	v_lshl_add_u64 v[48:49], v[44:45], 0, v[48:49]
	v_lshl_add_u64 v[50:51], v[44:45], 0, v[50:51]
	v_lshl_add_u64 v[52:53], v[44:45], 0, v[52:53]
	v_lshl_add_u64 v[54:55], v[44:45], 0, v[54:55]
	v_lshl_add_u64 v[56:57], v[44:45], 0, v[56:57]
	v_lshl_add_u64 v[58:59], v[44:45], 0, v[58:59]
	v_lshl_add_u64 v[44:45], v[44:45], 0, v[60:61]
	flat_load_dword v0, v[46:47] nt
	s_nop 0
	flat_load_dword v46, v[48:49] nt
	flat_load_dword v47, v[50:51] nt
	s_nop 0
	flat_load_dword v48, v[52:53] nt
	flat_load_dword v49, v[54:55] nt
	flat_load_dword v50, v[56:57] nt
	flat_load_dword v51, v[58:59] nt
	s_nop 0
	flat_load_dword v44, v[44:45] nt
	s_waitcnt vmcnt(0) lgkmcnt(0)
; #define LAS __attribute__((address_space(3)))
; __device__ __forceinline__ unsigned pk2(float lo, float hi) { return f2bf(lo) | (f2bf(hi) << 16); }
; __device__ __forceinline__ void tr_item(const float* W, int ldw, int k0, int n0, bf16* WT, size_t drow0, int ldk, float scale, LAS float* scr, int lane) {
;     ...
;     for (int i = 0; i < 32; ++i) scr[(2 * i + (lane >> 5)) * 33 + (lane & 31)] = wv[i];
;     asm volatile("s_waitcnt lgkmcnt(0)" ::: "memory");
;     const int c = lane & 7;
; #pragma unroll
;     for (int j = 0; j < 4; ++j) { const int n = (lane >> 3) + 8 * j; const LAS float* s = scr + (8 * c) * 33 + n;
;         u32x4 o; o.x = pk2(s[0 * 33] * scale, s[1 * 33] * scale); o.y = pk2(s[2 * 33] * scale, s[3 * 33] * scale); o.z = pk2(s[4 * 33] * scale, s[5 * 33] * scale); o.w = pk2(s[6 * 33] * scale, s[7 * 33] * scale);
;         *(u32x4*)(WT + (drow0 + n) * ldk + k0 + 8 * c) = o; }
	ds_write2_b32 v5, v33, v35 offset1:66
	ds_write2_b32 v5, v43, v62 offset0:132 offset1:198
	ds_write2_b32 v9, v63, v64 offset0:8 offset1:74
	ds_write2_b32 v9, v65, v66 offset0:140 offset1:206
	ds_write2_b32 v36, v67, v68 offset0:16 offset1:82
	ds_write2_b32 v36, v69, v70 offset0:148 offset1:214
	ds_write2_b32 v37, v71, v72 offset0:24 offset1:90
	ds_write2_b32 v37, v73, v74 offset0:156 offset1:222
	ds_write2_b32 v38, v75, v76 offset0:32 offset1:98
	ds_write2_b32 v38, v77, v78 offset0:164 offset1:230
	ds_write2_b32 v39, v79, v80 offset0:40 offset1:106
	ds_write2_b32 v39, v81, v82 offset0:172 offset1:238
	ds_write2_b32 v40, v0, v46 offset0:48 offset1:114
	ds_write2_b32 v40, v47, v48 offset0:180 offset1:246
	ds_write2_b32 v41, v49, v50 offset0:56 offset1:122
	ds_write2_b32 v41, v51, v44 offset0:188 offset1:254
	s_waitcnt lgkmcnt(0)
	ds_read2_b32 v[48:49], v7 offset1:8
	ds_read2_b32 v[52:53], v7 offset0:33 offset1:41
	ds_read2_b32 v[54:55], v7 offset0:66 offset1:74
	ds_read2_b32 v[56:57], v7 offset0:99 offset1:107
	ds_read2_b32 v[58:59], v7 offset0:132 offset1:140
	s_waitcnt lgkmcnt(4)
	v_bfe_u32 v0, v48, 16, 1
	v_add3_u32 v0, v48, v0, s52
	s_waitcnt lgkmcnt(3)
	v_bfe_u32 v33, v52, 16, 1
	v_lshrrev_b32_e32 v0, 16, v0
	v_add3_u32 v33, v52, v33, s52
	ds_read2_b32 v[60:61], v7 offset0:165 offset1:173
	v_and_or_b32 v44, v33, s53, v0
	s_waitcnt lgkmcnt(3)
	v_bfe_u32 v0, v54, 16, 1
	v_add3_u32 v0, v54, v0, s52
	s_waitcnt lgkmcnt(2)
	v_bfe_u32 v33, v56, 16, 1
	ds_read2_b32 v[62:63], v7 offset0:198 offset1:206
	v_lshrrev_b32_e32 v0, 16, v0
	v_add3_u32 v33, v56, v33, s52
	ds_read2_b32 v[64:65], v7 offset0:231 offset1:239
	v_and_or_b32 v45, v33, s53, v0
	s_waitcnt lgkmcnt(3)
	v_bfe_u32 v0, v58, 16, 1
	v_add3_u32 v0, v58, v0, s52
	s_waitcnt lgkmcnt(2)
	v_bfe_u32 v33, v60, 16, 1
	v_lshrrev_b32_e32 v0, 16, v0
	v_add3_u32 v33, v60, v33, s52
	v_and_or_b32 v46, v33, s53, v0
	s_waitcnt lgkmcnt(1)
	v_bfe_u32 v0, v62, 16, 1
	v_add3_u32 v0, v62, v0, s52
	s_waitcnt lgkmcnt(0)
	v_bfe_u32 v33, v64, 16, 1
	v_lshrrev_b32_e32 v0, 16, v0
	v_add3_u32 v33, v64, v33, s52
	s_mov_b32 s27, s25
	v_and_or_b32 v47, v33, s53, v0
	v_or_b32_e32 v0, s28, v2
	v_lshl_add_u64 v[50:51], s[26:27], 1, v[26:27]
	v_lshlrev_b32_e32 v0, 12, v0
	v_lshl_add_u64 v[66:67], v[50:51], 0, v[0:1]
	v_bfe_u32 v0, v49, 16, 1
	v_add3_u32 v0, v49, v0, s52
	v_bfe_u32 v33, v53, 16, 1
	v_lshrrev_b32_e32 v0, 16, v0
	v_add3_u32 v33, v53, v33, s52
	global_store_dwordx4 v[66:67], v[44:47], off
	ds_read2_b32 v[48:49], v7 offset0:16 offset1:24
	s_nop 0
	v_and_or_b32 v44, v33, s53, v0
	v_bfe_u32 v0, v55, 16, 1
	v_add3_u32 v0, v55, v0, s52
	v_bfe_u32 v33, v57, 16, 1
	v_lshrrev_b32_e32 v0, 16, v0
	v_add3_u32 v33, v57, v33, s52
	v_and_or_b32 v45, v33, s53, v0
	v_bfe_u32 v0, v59, 16, 1
	v_add3_u32 v0, v59, v0, s52
	v_bfe_u32 v33, v61, 16, 1
	v_lshrrev_b32_e32 v0, 16, v0
	v_add3_u32 v33, v61, v33, s52
	v_and_or_b32 v46, v33, s53, v0
	v_bfe_u32 v0, v63, 16, 1
	v_add3_u32 v0, v63, v0, s52
	v_bfe_u32 v33, v65, 16, 1
	v_lshrrev_b32_e32 v0, 16, v0
	v_add3_u32 v33, v65, v33, s52
	v_and_or_b32 v47, v33, s53, v0
	v_or_b32_e32 v0, s28, v4
	v_lshlrev_b32_e32 v0, 12, v0
	v_lshl_add_u64 v[52:53], v[50:51], 0, v[0:1]
	global_store_dwordx4 v[52:53], v[44:47], off
	ds_read2_b32 v[52:53], v7 offset0:49 offset1:57
	ds_read2_b32 v[54:55], v7 offset0:82 offset1:90
	ds_read2_b32 v[56:57], v7 offset0:115 offset1:123
	s_waitcnt lgkmcnt(3)
	v_bfe_u32 v0, v48, 16, 1
	v_add3_u32 v0, v48, v0, s52
	s_waitcnt lgkmcnt(2)
	v_bfe_u32 v33, v52, 16, 1
	ds_read2_b32 v[58:59], v7 offset0:148 offset1:156
	v_lshrrev_b32_e32 v0, 16, v0
	v_add3_u32 v33, v52, v33, s52
	ds_read2_b32 v[60:61], v7 offset0:181 offset1:189
	v_and_or_b32 v44, v33, s53, v0
	s_waitcnt lgkmcnt(3)
	v_bfe_u32 v0, v54, 16, 1
	v_add3_u32 v0, v54, v0, s52
	s_waitcnt lgkmcnt(2)
	v_bfe_u32 v33, v56, 16, 1
	ds_read2_b32 v[62:63], v7 offset0:214 offset1:222
	v_lshrrev_b32_e32 v0, 16, v0
	v_add3_u32 v33, v56, v33, s52
	ds_read2_b32 v[64:65], v7 offset0:247 offset1:255
	v_and_or_b32 v45, v33, s53, v0
	s_waitcnt lgkmcnt(3)
	v_bfe_u32 v0, v58, 16, 1
	v_add3_u32 v0, v58, v0, s52
	s_waitcnt lgkmcnt(2)
	v_bfe_u32 v33, v60, 16, 1
	v_lshrrev_b32_e32 v0, 16, v0
	v_add3_u32 v33, v60, v33, s52
	v_and_or_b32 v46, v33, s53, v0
	s_waitcnt lgkmcnt(1)
	v_bfe_u32 v0, v62, 16, 1
	v_add3_u32 v0, v62, v0, s52
	s_waitcnt lgkmcnt(0)
	v_bfe_u32 v33, v64, 16, 1
	v_lshrrev_b32_e32 v0, 16, v0
	v_add3_u32 v33, v64, v33, s52
	v_and_or_b32 v47, v33, s53, v0
	v_or_b32_e32 v0, s28, v6
	v_lshlrev_b32_e32 v0, 12, v0
	v_lshl_add_u64 v[66:67], v[50:51], 0, v[0:1]
	v_bfe_u32 v0, v49, 16, 1
	v_add3_u32 v0, v49, v0, s52
	v_bfe_u32 v33, v53, 16, 1
	v_lshrrev_b32_e32 v0, 16, v0
	v_add3_u32 v33, v53, v33, s52
	global_store_dwordx4 v[66:67], v[44:47], off
	s_nop 1
	v_and_or_b32 v44, v33, s53, v0
	v_bfe_u32 v0, v55, 16, 1
	v_add3_u32 v0, v55, v0, s52
	v_bfe_u32 v33, v57, 16, 1
	v_lshrrev_b32_e32 v0, 16, v0
	v_add3_u32 v33, v57, v33, s52
	v_and_or_b32 v45, v33, s53, v0
	v_bfe_u32 v0, v59, 16, 1
	v_add3_u32 v0, v59, v0, s52
	v_bfe_u32 v33, v61, 16, 1
	v_lshrrev_b32_e32 v0, 16, v0
	v_add3_u32 v33, v61, v33, s52
	v_and_or_b32 v46, v33, s53, v0
	v_bfe_u32 v0, v63, 16, 1
	v_add3_u32 v0, v63, v0, s52
	v_bfe_u32 v33, v65, 16, 1
	v_lshrrev_b32_e32 v0, 16, v0
	v_add3_u32 v33, v65, v33, s52
	v_and_or_b32 v47, v33, s53, v0
	v_or_b32_e32 v0, s28, v8
	v_lshlrev_b32_e32 v0, 12, v0
	v_lshl_add_u64 v[48:49], v[50:51], 0, v[0:1]
	global_store_dwordx4 v[48:49], v[44:47], off
	s_waitcnt lgkmcnt(0)

; #define LAS __attribute__((address_space(3)))
; __device__ __forceinline__ unsigned pk2(float lo, float hi) { return f2bf(lo) | (f2bf(hi) << 16); }
; __device__ __forceinline__ void tr_item(const float* W, int ldw, int k0, int n0, bf16* WT, size_t drow0, int ldk, float scale, LAS float* scr, int lane) {
;     float wv[32];
; #pragma unroll
;     for (int i = 0; i < 32; ++i) wv[i] = W[(size_t)(k0 + 2 * i + (lane >> 5)) * ldw + n0 + (lane & 31)];
; #pragma unroll
;     for (int i = 0; i < 32; ++i) scr[(2 * i + (lane >> 5)) * 33 + (lane & 31)] = wv[i];
;     asm volatile("s_waitcnt lgkmcnt(0)" ::: "memory");
;     const int c = lane & 7;
; #pragma unroll
;     for (int j = 0; j < 4; ++j) { const int n = (lane >> 3) + 8 * j; const LAS float* s = scr + (8 * c) * 33 + n;
;         u32x4 o; o.x = pk2(s[0 * 33] * scale, s[1 * 33] * scale); o.y = pk2(s[2 * 33] * scale, s[3 * 33] * scale); o.z = pk2(s[4 * 33] * scale, s[5 * 33] * scale); o.w = pk2(s[6 * 33] * scale, s[7 * 33] * scale);
; __device__ __forceinline__ void p0_prologue(const P0Args& A, LAS unsigned char* lds, int gw, int NGW, int wave, int lane) {
;     ...
;         if (r < I_IN) { const int nb = IN_W / 32, k0 = 64 * (r / nb), n0 = 32 * (r % nb); tr_item(A.w_in, IN_W, k0, n0, A.Win, n0, D, (n0 >= QOFF && n0 < KOFF) ? QSCALE : 1.f, scr, lane); continue; } r -= I_IN;
.LBB0_44:
	s_mul_hi_i32 s24, s57, 0x66666667
	s_lshr_b32 s26, s24, 31
	s_ashr_i32 s24, s24, 6
	s_add_i32 s24, s24, s26
	s_mul_i32 s26, s24, 0xffffec00
	s_lshl_b32 s28, s24, 6
	s_add_i32 s26, s3, s26
	s_ashr_i32 s27, s26, 31
	v_or_b32_e32 v0, s28, v3
	v_lshl_add_u64 v[44:45], s[26:27], 2, v[28:29]
	v_or_b32_e32 v33, 2, v0
	v_mad_i64_i32 v[48:49], s[36:37], v33, s49, v[44:45]
	v_or_b32_e32 v33, 4, v0
	v_mad_i64_i32 v[50:51], s[36:37], v33, s49, v[44:45]
	v_or_b32_e32 v33, 6, v0
	v_mad_i64_i32 v[52:53], s[36:37], v33, s49, v[44:45]
	v_or_b32_e32 v33, 8, v0
	v_mad_i64_i32 v[54:55], s[36:37], v33, s49, v[44:45]
	v_or_b32_e32 v33, 10, v0
	v_mad_i64_i32 v[56:57], s[36:37], v33, s49, v[44:45]
	v_or_b32_e32 v33, 12, v0
	v_mad_i64_i32 v[58:59], s[36:37], v33, s49, v[44:45]
	v_or_b32_e32 v33, 14, v0
	v_mad_i64_i32 v[46:47], s[36:37], v0, s49, v[44:45]
	v_mad_i64_i32 v[60:61], s[36:37], v33, s49, v[44:45]
	flat_load_dword v33, v[46:47] nt
	flat_load_dword v35, v[48:49] nt
	flat_load_dword v43, v[50:51] nt
	flat_load_dword v62, v[52:53] nt
	flat_load_dword v63, v[54:55] nt
	flat_load_dword v64, v[56:57] nt
	flat_load_dword v65, v[58:59] nt
	flat_load_dword v66, v[60:61] nt
	v_or_b32_e32 v46, 16, v0
	v_or_b32_e32 v48, 18, v0
	v_or_b32_e32 v50, 20, v0
	v_or_b32_e32 v52, 22, v0
	v_or_b32_e32 v54, 24, v0
	v_or_b32_e32 v56, 26, v0
	v_or_b32_e32 v58, 28, v0
	v_or_b32_e32 v60, 30, v0
	v_mad_i64_i32 v[46:47], s[36:37], v46, s49, v[44:45]
	v_mad_i64_i32 v[48:49], s[36:37], v48, s49, v[44:45]
	v_mad_i64_i32 v[50:51], s[36:37], v50, s49, v[44:45]
	v_mad_i64_i32 v[52:53], s[36:37], v52, s49, v[44:45]
	v_mad_i64_i32 v[54:55], s[36:37], v54, s49, v[44:45]
	v_mad_i64_i32 v[56:57], s[36:37], v56, s49, v[44:45]
	v_mad_i64_i32 v[58:59], s[36:37], v58, s49, v[44:45]
	v_mad_i64_i32 v[60:61], s[36:37], v60, s49, v[44:45]
	flat_load_dword v67, v[46:47] nt
	flat_load_dword v68, v[48:49] nt
	flat_load_dword v69, v[50:51] nt
	flat_load_dword v70, v[52:53] nt
	flat_load_dword v71, v[54:55] nt
	flat_load_dword v72, v[56:57] nt
	flat_load_dword v73, v[58:59] nt
	flat_load_dword v74, v[60:61] nt
	v_or_b32_e32 v46, 32, v0
	v_or_b32_e32 v48, 34, v0
	v_or_b32_e32 v50, 36, v0
	v_or_b32_e32 v52, 38, v0
	v_or_b32_e32 v54, 40, v0
	v_or_b32_e32 v56, 42, v0
	v_or_b32_e32 v58, 44, v0
	v_or_b32_e32 v60, 46, v0
	v_mad_i64_i32 v[46:47], s[36:37], v46, s49, v[44:45]
	v_mad_i64_i32 v[48:49], s[36:37], v48, s49, v[44:45]
	v_mad_i64_i32 v[50:51], s[36:37], v50, s49, v[44:45]
	v_mad_i64_i32 v[52:53], s[36:37], v52, s49, v[44:45]
	v_mad_i64_i32 v[54:55], s[36:37], v54, s49, v[44:45]
	v_mad_i64_i32 v[56:57], s[36:37], v56, s49, v[44:45]
	v_mad_i64_i32 v[58:59], s[36:37], v58, s49, v[44:45]
	v_mad_i64_i32 v[60:61], s[36:37], v60, s49, v[44:45]
	flat_load_dword v75, v[46:47] nt
	flat_load_dword v76, v[48:49] nt
	flat_load_dword v77, v[50:51] nt
	flat_load_dword v78, v[52:53] nt
	flat_load_dword v79, v[54:55] nt
	flat_load_dword v80, v[56:57] nt
	flat_load_dword v81, v[58:59] nt
	s_nop 0
	flat_load_dword v60, v[60:61] nt
	v_or_b32_e32 v46, 48, v0
	v_or_b32_e32 v48, 50, v0
	v_or_b32_e32 v50, 52, v0
	v_or_b32_e32 v52, 54, v0
	v_or_b32_e32 v54, 56, v0
	v_or_b32_e32 v56, 58, v0
	v_or_b32_e32 v58, 60, v0
	v_or_b32_e32 v0, 62, v0
	v_mad_i64_i32 v[46:47], s[36:37], v46, s49, v[44:45]
	v_mad_i64_i32 v[48:49], s[36:37], v48, s49, v[44:45]
	v_mad_i64_i32 v[50:51], s[36:37], v50, s49, v[44:45]
	v_mad_i64_i32 v[52:53], s[36:37], v52, s49, v[44:45]
	v_mad_i64_i32 v[54:55], s[36:37], v54, s49, v[44:45]
	v_mad_i64_i32 v[56:57], s[36:37], v56, s49, v[44:45]
	v_mad_i64_i32 v[58:59], s[36:37], v58, s49, v[44:45]
	v_mad_i64_i32 v[44:45], s[36:37], v0, s49, v[44:45]
	flat_load_dword v46, v[46:47] nt
	s_nop 0
	flat_load_dword v47, v[48:49] nt
	s_nop 0
	flat_load_dword v48, v[50:51] nt
	flat_load_dword v49, v[52:53] nt
	s_nop 0
	flat_load_dword v50, v[54:55] nt
	flat_load_dword v51, v[56:57] nt
	flat_load_dword v52, v[58:59] nt
	s_nop 0
	flat_load_dword v44, v[44:45] nt
	s_waitcnt vmcnt(0) lgkmcnt(0)
	ds_write2_b32 v5, v33, v35 offset1:66
	ds_write2_b32 v5, v43, v62 offset0:132 offset1:198
	ds_write2_b32 v9, v63, v64 offset0:8 offset1:74
	ds_write2_b32 v9, v65, v66 offset0:140 offset1:206
	ds_write2_b32 v36, v67, v68 offset0:16 offset1:82
	ds_write2_b32 v36, v69, v70 offset0:148 offset1:214
	ds_write2_b32 v37, v71, v72 offset0:24 offset1:90
	ds_write2_b32 v37, v73, v74 offset0:156 offset1:222
	ds_write2_b32 v38, v75, v76 offset0:32 offset1:98
	ds_write2_b32 v38, v77, v78 offset0:164 offset1:230
	ds_write2_b32 v39, v79, v80 offset0:40 offset1:106
	ds_write2_b32 v39, v81, v60 offset0:172 offset1:238
	ds_write2_b32 v40, v46, v47 offset0:48 offset1:114
	ds_write2_b32 v40, v48, v49 offset0:180 offset1:246
	ds_write2_b32 v41, v50, v51 offset0:56 offset1:122
	ds_write2_b32 v41, v52, v44 offset0:188 offset1:254
	s_waitcnt lgkmcnt(0)
	s_mulk_i32 s24, 0xff60
	ds_read2_b32 v[48:49], v7 offset1:8
	ds_read2_b32 v[50:51], v7 offset0:66 offset1:74
	ds_read2_b32 v[54:55], v7 offset0:33 offset1:41
	ds_read2_b32 v[56:57], v7 offset0:99 offset1:107
	s_add_i32 s24, s57, s24
	ds_read2_b32 v[58:59], v7 offset0:132 offset1:140
	ds_read2_b32 v[60:61], v7 offset0:198 offset1:206
	s_andn2_b32 s24, s24, 31
	ds_read2_b32 v[62:63], v7 offset0:165 offset1:173
	ds_read2_b32 v[64:65], v7 offset0:231 offset1:239
	s_cmp_eq_u32 s24, 64
	s_cselect_b64 vcc, -1, 0
	v_cndmask_b32_e32 v0, 1.0, v42, vcc
	s_waitcnt lgkmcnt(5)
	v_mov_b32_e32 v46, v54
	s_waitcnt lgkmcnt(4)
	v_mov_b32_e32 v47, v56
	v_mov_b32_e32 v44, v48
	v_mov_b32_e32 v45, v50
	v_pk_mul_f32 v[46:47], v[0:1], v[46:47] op_sel_hi:[0,1]
	s_waitcnt lgkmcnt(3)
	v_mov_b32_e32 v66, v58
	s_waitcnt lgkmcnt(2)
; #define LAS __attribute__((address_space(3)))
; __device__ __forceinline__ unsigned pk2(float lo, float hi) { return f2bf(lo) | (f2bf(hi) << 16); }
; __device__ __forceinline__ void tr_item(const float* W, int ldw, int k0, int n0, bf16* WT, size_t drow0, int ldk, float scale, LAS float* scr, int lane) {
;     ...
;     for (int j = 0; j < 4; ++j) { const int n = (lane >> 3) + 8 * j; const LAS float* s = scr + (8 * c) * 33 + n;
;         u32x4 o; o.x = pk2(s[0 * 33] * scale, s[1 * 33] * scale); o.y = pk2(s[2 * 33] * scale, s[3 * 33] * scale); o.z = pk2(s[4 * 33] * scale, s[5 * 33] * scale); o.w = pk2(s[6 * 33] * scale, s[7 * 33] * scale);
;         *(u32x4*)(WT + (drow0 + n) * ldk + k0 + 8 * c) = o; }
	v_mov_b32_e32 v67, v60
	v_pk_mul_f32 v[44:45], v[0:1], v[44:45] op_sel_hi:[0,1]
	v_pk_mul_f32 v[66:67], v[0:1], v[66:67] op_sel_hi:[0,1]
	s_waitcnt lgkmcnt(1)
	v_mov_b32_e32 v68, v62
	s_waitcnt lgkmcnt(0)
	v_mov_b32_e32 v69, v64
	v_bfe_u32 v43, v47, 16, 1
	v_bfe_u32 v48, v46, 16, 1
	v_pk_mul_f32 v[68:69], v[0:1], v[68:69] op_sel_hi:[0,1]
	v_add3_u32 v48, v46, v48, s52
	v_add3_u32 v43, v47, v43, s52
	v_bfe_u32 v46, v44, 16, 1
	v_bfe_u32 v47, v45, 16, 1
	v_bfe_u32 v50, v66, 16, 1
	v_bfe_u32 v54, v67, 16, 1
	s_ashr_i32 s29, s28, 31
	v_bfe_u32 v33, v69, 16, 1
	v_bfe_u32 v35, v68, 16, 1
	v_add3_u32 v54, v67, v54, s52
	v_add3_u32 v50, v66, v50, s52
	v_add3_u32 v45, v45, v47, s52
	v_add3_u32 v44, v44, v46, s52
	v_mov_b32_e32 v67, s27
	v_or_b32_e32 v66, s26, v2
	v_lshl_add_u64 v[52:53], s[28:29], 1, v[30:31]
	v_add3_u32 v35, v68, v35, s52
	v_add3_u32 v33, v69, v33, s52
	v_lshrrev_b32_e32 v44, 16, v44
	v_lshrrev_b32_e32 v45, 16, v45
	v_lshrrev_b32_e32 v46, 16, v50
	v_lshrrev_b32_e32 v47, 16, v54
	v_lshlrev_b64 v[66:67], 12, v[66:67]
	v_and_or_b32 v47, v33, s53, v47
	v_and_or_b32 v46, v35, s53, v46
	v_and_or_b32 v45, v43, s53, v45
	v_and_or_b32 v44, v48, s53, v44
	v_lshl_add_u64 v[66:67], v[52:53], 0, v[66:67]
	v_mov_b32_e32 v50, v49
	v_mov_b32_e32 v64, v63
	global_store_dwordx4 v[66:67], v[44:47], off
	v_mov_b32_e32 v56, v55
	v_mov_b32_e32 v60, v59
	v_pk_mul_f32 v[44:45], v[0:1], v[50:51] op_sel_hi:[0,1]
	v_pk_mul_f32 v[50:51], v[0:1], v[64:65] op_sel_hi:[0,1]
	v_pk_mul_f32 v[46:47], v[0:1], v[56:57] op_sel_hi:[0,1]
	v_pk_mul_f32 v[48:49], v[0:1], v[60:61] op_sel_hi:[0,1]
	v_bfe_u32 v33, v51, 16, 1
	v_bfe_u32 v35, v50, 16, 1
	v_bfe_u32 v43, v47, 16, 1
	v_bfe_u32 v54, v46, 16, 1
	v_add3_u32 v35, v50, v35, s52
	v_add3_u32 v33, v51, v33, s52
	v_bfe_u32 v50, v48, 16, 1
	v_bfe_u32 v51, v49, 16, 1
	v_add3_u32 v54, v46, v54, s52
	v_add3_u32 v43, v47, v43, s52
	v_bfe_u32 v46, v44, 16, 1
	v_bfe_u32 v47, v45, 16, 1
	v_add3_u32 v49, v49, v51, s52
	v_add3_u32 v48, v48, v50, s52
	v_add3_u32 v45, v45, v47, s52
	v_add3_u32 v44, v44, v46, s52
	v_lshrrev_b32_e32 v46, 16, v48
	v_lshrrev_b32_e32 v47, 16, v49
	v_mov_b32_e32 v49, s27
	v_or_b32_e32 v48, s26, v4
	v_lshrrev_b32_e32 v44, 16, v44
	v_lshrrev_b32_e32 v45, 16, v45
	v_lshlrev_b64 v[48:49], 12, v[48:49]
	v_and_or_b32 v47, v33, s53, v47
	v_and_or_b32 v46, v35, s53, v46
	v_and_or_b32 v45, v43, s53, v45
	v_and_or_b32 v44, v54, s53, v44
	v_lshl_add_u64 v[48:49], v[52:53], 0, v[48:49]
	ds_read2_b32 v[50:51], v7 offset0:16 offset1:24
	ds_read2_b32 v[54:55], v7 offset0:82 offset1:90
	global_store_dwordx4 v[48:49], v[44:47], off
	ds_read2_b32 v[48:49], v7 offset0:49 offset1:57
	ds_read2_b32 v[56:57], v7 offset0:115 offset1:123
	ds_read2_b32 v[58:59], v7 offset0:148 offset1:156
	ds_read2_b32 v[60:61], v7 offset0:214 offset1:222
	ds_read2_b32 v[62:63], v7 offset0:181 offset1:189
	ds_read2_b32 v[64:65], v7 offset0:247 offset1:255
	s_waitcnt lgkmcnt(7)
	v_mov_b32_e32 v44, v50
	s_waitcnt lgkmcnt(5)
	v_mov_b32_e32 v46, v48
	s_waitcnt lgkmcnt(4)
	v_mov_b32_e32 v47, v56
	v_mov_b32_e32 v45, v54
	v_pk_mul_f32 v[46:47], v[0:1], v[46:47] op_sel_hi:[0,1]
	s_waitcnt lgkmcnt(3)
	v_mov_b32_e32 v66, v58
	s_waitcnt lgkmcnt(2)
	v_mov_b32_e32 v67, v60
	v_pk_mul_f32 v[44:45], v[0:1], v[44:45] op_sel_hi:[0,1]
	v_pk_mul_f32 v[66:67], v[0:1], v[66:67] op_sel_hi:[0,1]
	s_waitcnt lgkmcnt(1)
	v_mov_b32_e32 v68, v62
	s_waitcnt lgkmcnt(0)
	v_mov_b32_e32 v69, v64
	v_bfe_u32 v43, v47, 16, 1
	v_bfe_u32 v48, v46, 16, 1
	v_pk_mul_f32 v[68:69], v[0:1], v[68:69] op_sel_hi:[0,1]
	v_add3_u32 v48, v46, v48, s52
	v_add3_u32 v43, v47, v43, s52
	v_bfe_u32 v46, v44, 16, 1
	v_bfe_u32 v47, v45, 16, 1
	v_bfe_u32 v50, v66, 16, 1
	v_bfe_u32 v54, v67, 16, 1
	v_bfe_u32 v33, v69, 16, 1
	v_bfe_u32 v35, v68, 16, 1
	v_add3_u32 v54, v67, v54, s52
	v_add3_u32 v50, v66, v50, s52
	v_add3_u32 v45, v45, v47, s52
	v_add3_u32 v44, v44, v46, s52
	v_mov_b32_e32 v67, s27
	v_or_b32_e32 v66, s26, v6
	v_add3_u32 v35, v68, v35, s52
	v_add3_u32 v33, v69, v33, s52
	v_lshrrev_b32_e32 v44, 16, v44
	v_lshrrev_b32_e32 v45, 16, v45
	v_lshrrev_b32_e32 v46, 16, v50
	v_lshrrev_b32_e32 v47, 16, v54
	v_lshlrev_b64 v[66:67], 12, v[66:67]
	v_mov_b32_e32 v64, v63
	v_and_or_b32 v47, v33, s53, v47
	v_and_or_b32 v46, v35, s53, v46
	v_and_or_b32 v45, v43, s53, v45
	v_and_or_b32 v44, v48, s53, v44
	v_lshl_add_u64 v[66:67], v[52:53], 0, v[66:67]
	v_mov_b32_e32 v54, v51
	v_mov_b32_e32 v56, v49
	v_mov_b32_e32 v60, v59
	v_pk_mul_f32 v[50:51], v[0:1], v[64:65] op_sel_hi:[0,1]
	global_store_dwordx4 v[66:67], v[44:47], off
	v_pk_mul_f32 v[48:49], v[0:1], v[60:61] op_sel_hi:[0,1]
	v_bfe_u32 v33, v50, 16, 1
	v_pk_mul_f32 v[44:45], v[0:1], v[54:55] op_sel_hi:[0,1]
	v_pk_mul_f32 v[46:47], v[0:1], v[56:57] op_sel_hi:[0,1]
	v_bfe_u32 v0, v51, 16, 1
	v_bfe_u32 v35, v47, 16, 1
	v_bfe_u32 v43, v46, 16, 1
	v_add3_u32 v33, v50, v33, s52
	v_add3_u32 v0, v51, v0, s52
	v_bfe_u32 v50, v48, 16, 1
	v_bfe_u32 v51, v49, 16, 1
	v_add3_u32 v43, v46, v43, s52
	v_add3_u32 v35, v47, v35, s52
	v_bfe_u32 v46, v44, 16, 1
	v_bfe_u32 v47, v45, 16, 1
	v_add3_u32 v49, v49, v51, s52
	v_add3_u32 v48, v48, v50, s52
	v_add3_u32 v45, v45, v47, s52
	v_add3_u32 v44, v44, v46, s52
	v_lshrrev_b32_e32 v46, 16, v48
	v_lshrrev_b32_e32 v47, 16, v49
	v_mov_b32_e32 v49, s27
	v_or_b32_e32 v48, s26, v8
	v_lshrrev_b32_e32 v44, 16, v44
	v_lshrrev_b32_e32 v45, 16, v45
	v_lshlrev_b64 v[48:49], 12, v[48:49]
	v_and_or_b32 v47, v0, s53, v47
	v_and_or_b32 v46, v33, s53, v46
	v_and_or_b32 v45, v35, s53, v45
	v_and_or_b32 v44, v43, s53, v44
	v_lshl_add_u64 v[48:49], v[52:53], 0, v[48:49]
	global_store_dwordx4 v[48:49], v[44:47], off
	s_waitcnt lgkmcnt(0)
	s_branch .LBB0_20

; __device__ __forceinline__ void conv_bf16(const float* src, bf16* dst, size_t nsteps, int gw, int NGW, int lane) {
;     ...
;     for (size_t st = (size_t)gw; st < nsteps; st += (size_t)4 * NGW) { f32x4 a[4], b[4];
; #pragma unroll
;         for (int k = 0; k < 4; ++k) { const size_t s = st + (size_t)k * NGW; if (s < nsteps) { const float* q = src + s * 512 + lane * 4; a[k] = *(const f32x4*)q; b[k] = *(const f32x4*)(q + 256); } }
.LBB0_48:
	flat_load_dwordx4 v[28:31], v[34:35] nt
	flat_load_dwordx4 v[24:27], v[34:35] offset:1024 nt
	s_add_u32 s10, s56, s54
	s_addc_u32 s11, s57, s55
	v_cmp_gt_u64_e32 vcc, s[10:11], v[40:41]
	v_cmp_lt_u64_e64 s[8:9], s[10:11], v[38:39]
	s_cbranch_vccnz .LBB0_50
	flat_load_dwordx4 v[0:3], v[36:37] nt
	flat_load_dwordx4 v[12:15], v[36:37] offset:1024 nt
.LBB0_50:
	s_add_u32 s12, s30, s54
	s_addc_u32 s13, s31, s55
	v_cmp_gt_u64_e32 vcc, s[12:13], v[40:41]
	v_cmp_lt_u64_e64 s[10:11], s[12:13], v[38:39]
	s_cbranch_vccnz .LBB0_52
	v_lshl_add_u64 v[16:17], v[34:35], 0, s[28:29]
	flat_load_dwordx4 v[4:7], v[16:17] nt
	s_nop 0
	flat_load_dwordx4 v[16:19], v[16:17] offset:1024 nt
.LBB0_52:
	s_add_u32 s36, s62, s54
	s_addc_u32 s37, s3, s55
	v_cmp_gt_u64_e32 vcc, s[36:37], v[40:41]
	v_cmp_lt_u64_e64 s[12:13], s[36:37], v[38:39]
	s_cbranch_vccnz .LBB0_54
	v_lshl_add_u64 v[20:21], v[34:35], 0, s[22:23]
	flat_load_dwordx4 v[8:11], v[20:21] nt
	s_nop 0
	flat_load_dwordx4 v[20:23], v[20:21] offset:1024 nt

; __device__ __forceinline__ void conv_bf16(const float* src, bf16* dst, size_t nsteps, int gw, int NGW, int lane) {
;     ...
;     for (size_t st = (size_t)gw; st < nsteps; st += (size_t)4 * NGW) { f32x4 a[4], b[4];
; #pragma unroll
;         for (int k = 0; k < 4; ++k) { const size_t s = st + (size_t)k * NGW; if (s < nsteps) { const float* q = src + s * 512 + lane * 4; a[k] = *(const f32x4*)q; b[k] = *(const f32x4*)(q + 256); } }
; __device__ __forceinline__ void p0_prologue(const P0Args& A, LAS unsigned char* lds, int gw, int NGW, int wave, int lane) {
;     ...
;     conv_bf16(A.p, A.pb, (size_t)M * PLE / 512, gw, NGW, lane);
.LBB0_63:
	flat_load_dwordx4 v[28:31], v[34:35] nt
	flat_load_dwordx4 v[24:27], v[34:35] offset:1024 nt
	s_add_u32 s10, s56, s14
	s_addc_u32 s11, s57, s15
	v_cmp_gt_u64_e32 vcc, s[10:11], v[40:41]
	v_cmp_lt_u64_e64 s[8:9], s[10:11], v[38:39]
	s_cbranch_vccnz .LBB0_65
	flat_load_dwordx4 v[0:3], v[36:37] nt
	flat_load_dwordx4 v[12:15], v[36:37] offset:1024 nt
.LBB0_65:
	s_add_u32 s12, s30, s14
	s_addc_u32 s13, s31, s15
	v_cmp_gt_u64_e32 vcc, s[12:13], v[40:41]
	v_cmp_lt_u64_e64 s[10:11], s[12:13], v[38:39]
	s_cbranch_vccnz .LBB0_67
	v_lshl_add_u64 v[16:17], v[34:35], 0, s[28:29]
	flat_load_dwordx4 v[4:7], v[16:17] nt
	s_nop 0
	flat_load_dwordx4 v[16:19], v[16:17] offset:1024 nt
.LBB0_67:
	s_add_u32 s36, s62, s14
	s_addc_u32 s37, s3, s15
	v_cmp_gt_u64_e32 vcc, s[36:37], v[40:41]
	v_cmp_lt_u64_e64 s[12:13], s[36:37], v[38:39]
	s_cbranch_vccnz .LBB0_69
	v_lshl_add_u64 v[20:21], v[34:35], 0, s[22:23]
	flat_load_dwordx4 v[8:11], v[20:21] nt
	s_nop 0
	flat_load_dwordx4 v[20:23], v[20:21] offset:1024 nt
